# hand-scheduled TB=16 scan inner loops (GDN+RWKV), LDS operands prefetched one step ahead
# speedup vs baseline: 1.0245x; 1.0245x over previous
; #define LAS __attribute__((address_space(3)))
; __device__ __forceinline__ f32x2 fma2(f32x2 a, f32x2 b, f32x2 c) { return __builtin_elementwise_fma(a, b, c); }
; __device__ __forceinline__ float sum8(float x) { x += dppf<0x141>(x); x += dppf<0x4E>(x); x += dppf<0xB1>(x); return x; }
; __device__ __forceinline__ GOps8 g_ld8(const LAS float* B, int t, int kq, int vidx) {
;     GOps8 o; const LAS float* V = B + t * 256 + kq * 16;
; #pragma unroll
;     for (int h = 0; h < 4; ++h) { o.q[h] = *(const LAS f32x4*)(V + 4 * h); o.k[h] = *(const LAS f32x4*)(V + 128 + 4 * h); }
;     o.v = B[4096 + t * 16 + vidx]; o.sc = *(const LAS f32x4*)(B + 4352 + t * 4); return o;
; }
; template <int TB> __device__ __forceinline__ void gdn_block8(f32x2 (&S)[8], const LAS float* B, int kq, int vidx, float* oo) {
;     float okA = 0.f, okB = 0.f;
;     GOps8 c = g_ld8(B, 0, kq, vidx);
; #pragma unroll 1
;     for (int t0 = 0; t0 < TB; t0 += SCAN_UNR) {
;         float P = 1.f, iP = 1.f;
; #pragma unroll
;         for (int tt = 0; tt < SCAN_UNR; ++tt) {
;             const int t = t0 + tt;
;             const GOps8 n = g_ld8(B, (t + 1) & 15, kq, vidx);
;             const f32x2 k[8] = PAIRS8(c.k), q[8] = PAIRS8(c.q);
;             f32x2 pk = S[0] * k[0], pq = S[0] * q[0];
; #pragma unroll
;             for (int e = 1; e < 8; ++e) { pk = fma2(S[e], k[e], pk); pq = fma2(S[e], q[e], pq); }
;             const float dk = sum8(pk.x + pk.y), dq = sum8(pq.x + pq.y);
;             P *= c.sc.x; iP *= c.sc.w;
;             const float coef = c.sc.y * (c.v - P * dk);
;             const float cs = coef * iP; const f32x2 cf2 = {cs, cs};
; #pragma unroll
;             for (int e = 0; e < 8; ++e) S[e] = fma2(k[e], cf2, S[e]);
;             const float o = P * dq + c.sc.z * coef;
;             okA = (kq == t) ? o : okA; okB = (kq + 8 == t) ? o : okB;
;             c = n;
;         }
;         const f32x2 p2 = {P, P};
; #pragma unroll
;         for (int e = 0; e < 8; ++e) S[e] = S[e] * p2;
;     }
;     oo[(size_t)kq * GW] = okA;
;     if (TB == 16) oo[(size_t)(kq + 8) * GW] = okB;
; }
.LBB0_984:
	v_mov_b32_e32 v97, s48
	ds_read_b128 v[64:67], v159 offset:512
	ds_read_b128 v[48:51], v159 offset:0
	ds_read_b128 v[68:71], v159 offset:528
	ds_read_b128 v[52:55], v159 offset:16
	ds_read_b128 v[72:75], v159 offset:544
	ds_read_b128 v[56:59], v159 offset:32
	ds_read_b128 v[76:79], v159 offset:560
	ds_read_b128 v[60:63], v159 offset:48
	ds_read_b128 v[80:83], v97 offset:0
	ds_read_b32 v84, v160 offset:16384
	ds_read_b128 v[194:197], v159 offset:1536
	ds_read_b128 v[178:181], v159 offset:1024
	ds_read_b128 v[198:201], v159 offset:1552
	ds_read_b128 v[182:185], v159 offset:1040
	ds_read_b128 v[202:205], v159 offset:1568
	ds_read_b128 v[186:189], v159 offset:1056
	ds_read_b128 v[206:209], v159 offset:1584
	s_waitcnt lgkmcnt(7)
	v_pk_mul_f32 v[86:87], v[108:109], v[64:65]
	v_pk_mul_f32 v[88:89], v[108:109], v[48:49]
	v_pk_fma_f32 v[86:87], v[110:111], v[66:67], v[86:87]
	v_pk_fma_f32 v[88:89], v[110:111], v[50:51], v[88:89]
	v_pk_fma_f32 v[86:87], v[112:113], v[68:69], v[86:87]
	v_pk_fma_f32 v[88:89], v[112:113], v[52:53], v[88:89]
	v_pk_fma_f32 v[86:87], v[114:115], v[70:71], v[86:87]
	v_pk_fma_f32 v[88:89], v[114:115], v[54:55], v[88:89]
	v_pk_fma_f32 v[86:87], v[116:117], v[72:73], v[86:87]
	v_pk_fma_f32 v[88:89], v[116:117], v[56:57], v[88:89]
	v_pk_fma_f32 v[86:87], v[118:119], v[74:75], v[86:87]
	v_pk_fma_f32 v[88:89], v[118:119], v[58:59], v[88:89]
	v_pk_fma_f32 v[86:87], v[120:121], v[76:77], v[86:87]
	v_pk_fma_f32 v[88:89], v[120:121], v[60:61], v[88:89]
	v_pk_fma_f32 v[86:87], v[122:123], v[78:79], v[86:87]
	v_pk_fma_f32 v[88:89], v[122:123], v[62:63], v[88:89]
	v_add_f32_e32 v86, v86, v87
	v_add_f32_e32 v88, v88, v89
	ds_read_b128 v[190:193], v159 offset:1072
	v_add_f32_dpp v86, v86, v86 row_half_mirror row_mask:0xf bank_mask:0xf bound_ctrl:1
	v_add_f32_dpp v88, v88, v88 row_half_mirror row_mask:0xf bank_mask:0xf bound_ctrl:1
	ds_read_b128 v[210:213], v97 offset:16
	v_add_f32_dpp v86, v86, v86 quad_perm:[2,3,0,1] row_mask:0xf bank_mask:0xf bound_ctrl:1
	v_add_f32_dpp v88, v88, v88 quad_perm:[2,3,0,1] row_mask:0xf bank_mask:0xf bound_ctrl:1
	ds_read_b32 v214, v160 offset:16448
	v_add_f32_dpp v86, v86, v86 quad_perm:[1,0,3,2] row_mask:0xf bank_mask:0xf bound_ctrl:1
	v_add_f32_dpp v88, v88, v88 quad_perm:[1,0,3,2] row_mask:0xf bank_mask:0xf bound_ctrl:1
	v_fma_f32 v94, -v80, v86, v84
	v_mul_f32_e32 v95, v80, v88
	v_mul_f32_e32 v94, v81, v94
	v_cmp_eq_u32_e32 vcc, 0, v156
	v_mul_f32_e32 v92, v94, v83
	v_fma_f32 v96, v82, v94, v95
	v_pk_fma_f32 v[108:109], v[64:65], v[92:93], v[108:109] op_sel_hi:[1,0,1]
	v_pk_fma_f32 v[110:111], v[66:67], v[92:93], v[110:111] op_sel_hi:[1,0,1]
	v_cndmask_b32_e32 v37, v37, v96, vcc
	v_pk_fma_f32 v[112:113], v[68:69], v[92:93], v[112:113] op_sel_hi:[1,0,1]
	v_pk_fma_f32 v[114:115], v[70:71], v[92:93], v[114:115] op_sel_hi:[1,0,1]
	v_pk_fma_f32 v[116:117], v[72:73], v[92:93], v[116:117] op_sel_hi:[1,0,1]
	v_pk_fma_f32 v[118:119], v[74:75], v[92:93], v[118:119] op_sel_hi:[1,0,1]
	v_pk_fma_f32 v[120:121], v[76:77], v[92:93], v[120:121] op_sel_hi:[1,0,1]
	v_pk_fma_f32 v[122:123], v[78:79], v[92:93], v[122:123] op_sel_hi:[1,0,1]
	ds_read_b128 v[64:67], v159 offset:2560
	ds_read_b128 v[48:51], v159 offset:2048
	ds_read_b128 v[68:71], v159 offset:2576
	ds_read_b128 v[52:55], v159 offset:2064
	ds_read_b128 v[72:75], v159 offset:2592
	ds_read_b128 v[56:59], v159 offset:2080
	ds_read_b128 v[76:79], v159 offset:2608
	s_waitcnt lgkmcnt(7)
	v_pk_mul_f32 v[86:87], v[108:109], v[194:195]
	v_pk_mul_f32 v[88:89], v[108:109], v[178:179]
	v_pk_fma_f32 v[86:87], v[110:111], v[196:197], v[86:87]
	v_pk_fma_f32 v[88:89], v[110:111], v[180:181], v[88:89]
	v_pk_fma_f32 v[86:87], v[112:113], v[198:199], v[86:87]
	v_pk_fma_f32 v[88:89], v[112:113], v[182:183], v[88:89]
	v_mul_f32_e32 v90, v80, v210
	v_mul_f32_e32 v91, v83, v213
	v_pk_fma_f32 v[86:87], v[114:115], v[200:201], v[86:87]
	v_pk_fma_f32 v[88:89], v[114:115], v[184:185], v[88:89]
	v_pk_fma_f32 v[86:87], v[116:117], v[202:203], v[86:87]
	v_pk_fma_f32 v[88:89], v[116:117], v[186:187], v[88:89]
	v_pk_fma_f32 v[86:87], v[118:119], v[204:205], v[86:87]
	v_pk_fma_f32 v[88:89], v[118:119], v[188:189], v[88:89]
	v_pk_fma_f32 v[86:87], v[120:121], v[206:207], v[86:87]
	v_pk_fma_f32 v[88:89], v[120:121], v[190:191], v[88:89]
	v_pk_fma_f32 v[86:87], v[122:123], v[208:209], v[86:87]
	v_pk_fma_f32 v[88:89], v[122:123], v[192:193], v[88:89]
	v_add_f32_e32 v86, v86, v87
	v_add_f32_e32 v88, v88, v89
	ds_read_b128 v[60:63], v159 offset:2096
	v_add_f32_dpp v86, v86, v86 row_half_mirror row_mask:0xf bank_mask:0xf bound_ctrl:1
	v_add_f32_dpp v88, v88, v88 row_half_mirror row_mask:0xf bank_mask:0xf bound_ctrl:1
	ds_read_b128 v[80:83], v97 offset:32
	v_add_f32_dpp v86, v86, v86 quad_perm:[2,3,0,1] row_mask:0xf bank_mask:0xf bound_ctrl:1
	v_add_f32_dpp v88, v88, v88 quad_perm:[2,3,0,1] row_mask:0xf bank_mask:0xf bound_ctrl:1
	ds_read_b32 v84, v160 offset:16512
	v_add_f32_dpp v86, v86, v86 quad_perm:[1,0,3,2] row_mask:0xf bank_mask:0xf bound_ctrl:1
	v_add_f32_dpp v88, v88, v88 quad_perm:[1,0,3,2] row_mask:0xf bank_mask:0xf bound_ctrl:1
	v_fma_f32 v94, -v90, v86, v214
	v_mul_f32_e32 v95, v90, v88
	v_mul_f32_e32 v94, v211, v94
	v_cmp_eq_u32_e32 vcc, 1, v156
	v_mul_f32_e32 v92, v94, v91
	v_fma_f32 v96, v212, v94, v95
	v_pk_fma_f32 v[108:109], v[194:195], v[92:93], v[108:109] op_sel_hi:[1,0,1]
	v_pk_fma_f32 v[110:111], v[196:197], v[92:93], v[110:111] op_sel_hi:[1,0,1]
	v_cndmask_b32_e32 v37, v37, v96, vcc
	v_pk_fma_f32 v[112:113], v[198:199], v[92:93], v[112:113] op_sel_hi:[1,0,1]
	v_pk_fma_f32 v[114:115], v[200:201], v[92:93], v[114:115] op_sel_hi:[1,0,1]
	v_pk_fma_f32 v[116:117], v[202:203], v[92:93], v[116:117] op_sel_hi:[1,0,1]
	v_pk_fma_f32 v[118:119], v[204:205], v[92:93], v[118:119] op_sel_hi:[1,0,1]
	v_pk_fma_f32 v[120:121], v[206:207], v[92:93], v[120:121] op_sel_hi:[1,0,1]
	v_pk_fma_f32 v[122:123], v[208:209], v[92:93], v[122:123] op_sel_hi:[1,0,1]
	ds_read_b128 v[194:197], v159 offset:3584
	ds_read_b128 v[178:181], v159 offset:3072
	ds_read_b128 v[198:201], v159 offset:3600
	ds_read_b128 v[182:185], v159 offset:3088
	ds_read_b128 v[202:205], v159 offset:3616
	ds_read_b128 v[186:189], v159 offset:3104
	ds_read_b128 v[206:209], v159 offset:3632
	s_waitcnt lgkmcnt(7)
; __device__ __forceinline__ f32x2 fma2(f32x2 a, f32x2 b, f32x2 c) { return __builtin_elementwise_fma(a, b, c); }
; __device__ __forceinline__ float sum8(float x) { x += dppf<0x141>(x); x += dppf<0x4E>(x); x += dppf<0xB1>(x); return x; }
; template <int TB> __device__ __forceinline__ void gdn_block8(f32x2 (&S)[8], const LAS float* B, int kq, int vidx, float* oo) {
;     ...
;     for (int t0 = 0; t0 < TB; t0 += SCAN_UNR) {
;         float P = 1.f, iP = 1.f;
; #pragma unroll
;         for (int tt = 0; tt < SCAN_UNR; ++tt) {
;             const int t = t0 + tt;
;             const GOps8 n = g_ld8(B, (t + 1) & 15, kq, vidx);
;             const f32x2 k[8] = PAIRS8(c.k), q[8] = PAIRS8(c.q);
;             f32x2 pk = S[0] * k[0], pq = S[0] * q[0];
; #pragma unroll
;             for (int e = 1; e < 8; ++e) { pk = fma2(S[e], k[e], pk); pq = fma2(S[e], q[e], pq); }
;             const float dk = sum8(pk.x + pk.y), dq = sum8(pq.x + pq.y);
;             P *= c.sc.x; iP *= c.sc.w;
;             const float coef = c.sc.y * (c.v - P * dk);
;             const float cs = coef * iP; const f32x2 cf2 = {cs, cs};
; #pragma unroll
;             for (int e = 0; e < 8; ++e) S[e] = fma2(k[e], cf2, S[e]);
;             const float o = P * dq + c.sc.z * coef;
;             okA = (kq == t) ? o : okA; okB = (kq + 8 == t) ? o : okB;
;             c = n;
;         }
;         const f32x2 p2 = {P, P};
; #pragma unroll
;         for (int e = 0; e < 8; ++e) S[e] = S[e] * p2;
	v_pk_mul_f32 v[86:87], v[108:109], v[64:65]
	v_pk_mul_f32 v[88:89], v[108:109], v[48:49]
	v_pk_fma_f32 v[86:87], v[110:111], v[66:67], v[86:87]
	v_pk_fma_f32 v[88:89], v[110:111], v[50:51], v[88:89]
	v_pk_fma_f32 v[86:87], v[112:113], v[68:69], v[86:87]
	v_pk_fma_f32 v[88:89], v[112:113], v[52:53], v[88:89]
	v_mul_f32_e32 v90, v90, v80
	v_mul_f32_e32 v91, v91, v83
	v_pk_fma_f32 v[86:87], v[114:115], v[70:71], v[86:87]
	v_pk_fma_f32 v[88:89], v[114:115], v[54:55], v[88:89]
	v_pk_fma_f32 v[86:87], v[116:117], v[72:73], v[86:87]
	v_pk_fma_f32 v[88:89], v[116:117], v[56:57], v[88:89]
	v_pk_fma_f32 v[86:87], v[118:119], v[74:75], v[86:87]
	v_pk_fma_f32 v[88:89], v[118:119], v[58:59], v[88:89]
	v_pk_fma_f32 v[86:87], v[120:121], v[76:77], v[86:87]
	v_pk_fma_f32 v[88:89], v[120:121], v[60:61], v[88:89]
	v_pk_fma_f32 v[86:87], v[122:123], v[78:79], v[86:87]
	v_pk_fma_f32 v[88:89], v[122:123], v[62:63], v[88:89]
	v_add_f32_e32 v86, v86, v87
	v_add_f32_e32 v88, v88, v89
	ds_read_b128 v[190:193], v159 offset:3120
	v_add_f32_dpp v86, v86, v86 row_half_mirror row_mask:0xf bank_mask:0xf bound_ctrl:1
	v_add_f32_dpp v88, v88, v88 row_half_mirror row_mask:0xf bank_mask:0xf bound_ctrl:1
	ds_read_b128 v[210:213], v97 offset:48
	v_add_f32_dpp v86, v86, v86 quad_perm:[2,3,0,1] row_mask:0xf bank_mask:0xf bound_ctrl:1
	v_add_f32_dpp v88, v88, v88 quad_perm:[2,3,0,1] row_mask:0xf bank_mask:0xf bound_ctrl:1
	ds_read_b32 v214, v160 offset:16576
	v_add_f32_dpp v86, v86, v86 quad_perm:[1,0,3,2] row_mask:0xf bank_mask:0xf bound_ctrl:1
	v_add_f32_dpp v88, v88, v88 quad_perm:[1,0,3,2] row_mask:0xf bank_mask:0xf bound_ctrl:1
	v_fma_f32 v94, -v90, v86, v84
	v_mul_f32_e32 v95, v90, v88
	v_mul_f32_e32 v94, v81, v94
	v_cmp_eq_u32_e32 vcc, 2, v156
	v_mul_f32_e32 v92, v94, v91
	v_fma_f32 v96, v82, v94, v95
	v_pk_fma_f32 v[108:109], v[64:65], v[92:93], v[108:109] op_sel_hi:[1,0,1]
	v_pk_fma_f32 v[110:111], v[66:67], v[92:93], v[110:111] op_sel_hi:[1,0,1]
	v_cndmask_b32_e32 v37, v37, v96, vcc
	v_pk_fma_f32 v[112:113], v[68:69], v[92:93], v[112:113] op_sel_hi:[1,0,1]
	v_pk_fma_f32 v[114:115], v[70:71], v[92:93], v[114:115] op_sel_hi:[1,0,1]
	v_pk_fma_f32 v[116:117], v[72:73], v[92:93], v[116:117] op_sel_hi:[1,0,1]
	v_pk_fma_f32 v[118:119], v[74:75], v[92:93], v[118:119] op_sel_hi:[1,0,1]
	v_pk_fma_f32 v[120:121], v[76:77], v[92:93], v[120:121] op_sel_hi:[1,0,1]
	v_pk_fma_f32 v[122:123], v[78:79], v[92:93], v[122:123] op_sel_hi:[1,0,1]
	ds_read_b128 v[64:67], v159 offset:4608
	ds_read_b128 v[48:51], v159 offset:4096
	ds_read_b128 v[68:71], v159 offset:4624
	ds_read_b128 v[52:55], v159 offset:4112
	ds_read_b128 v[72:75], v159 offset:4640
	ds_read_b128 v[56:59], v159 offset:4128
	ds_read_b128 v[76:79], v159 offset:4656
	s_waitcnt lgkmcnt(7)
	v_pk_mul_f32 v[86:87], v[108:109], v[194:195]
	v_pk_mul_f32 v[88:89], v[108:109], v[178:179]
	v_pk_fma_f32 v[86:87], v[110:111], v[196:197], v[86:87]
	v_pk_fma_f32 v[88:89], v[110:111], v[180:181], v[88:89]
	v_pk_fma_f32 v[86:87], v[112:113], v[198:199], v[86:87]
	v_pk_fma_f32 v[88:89], v[112:113], v[182:183], v[88:89]
	v_mul_f32_e32 v90, v90, v210
	v_mul_f32_e32 v91, v91, v213
	v_pk_fma_f32 v[86:87], v[114:115], v[200:201], v[86:87]
	v_pk_fma_f32 v[88:89], v[114:115], v[184:185], v[88:89]
	v_pk_fma_f32 v[86:87], v[116:117], v[202:203], v[86:87]
	v_pk_fma_f32 v[88:89], v[116:117], v[186:187], v[88:89]
	v_pk_fma_f32 v[86:87], v[118:119], v[204:205], v[86:87]
	v_pk_fma_f32 v[88:89], v[118:119], v[188:189], v[88:89]
	v_pk_fma_f32 v[86:87], v[120:121], v[206:207], v[86:87]
	v_pk_fma_f32 v[88:89], v[120:121], v[190:191], v[88:89]
	v_pk_fma_f32 v[86:87], v[122:123], v[208:209], v[86:87]
	v_pk_fma_f32 v[88:89], v[122:123], v[192:193], v[88:89]
	v_add_f32_e32 v86, v86, v87
	v_add_f32_e32 v88, v88, v89
	ds_read_b128 v[60:63], v159 offset:4144
	v_add_f32_dpp v86, v86, v86 row_half_mirror row_mask:0xf bank_mask:0xf bound_ctrl:1
	v_add_f32_dpp v88, v88, v88 row_half_mirror row_mask:0xf bank_mask:0xf bound_ctrl:1
	ds_read_b128 v[80:83], v97 offset:64
	v_add_f32_dpp v86, v86, v86 quad_perm:[2,3,0,1] row_mask:0xf bank_mask:0xf bound_ctrl:1
	v_add_f32_dpp v88, v88, v88 quad_perm:[2,3,0,1] row_mask:0xf bank_mask:0xf bound_ctrl:1
	ds_read_b32 v84, v160 offset:16640
	v_add_f32_dpp v86, v86, v86 quad_perm:[1,0,3,2] row_mask:0xf bank_mask:0xf bound_ctrl:1
	v_add_f32_dpp v88, v88, v88 quad_perm:[1,0,3,2] row_mask:0xf bank_mask:0xf bound_ctrl:1
	v_fma_f32 v94, -v90, v86, v214
	v_mul_f32_e32 v95, v90, v88
	v_mul_f32_e32 v94, v211, v94
	v_cmp_eq_u32_e32 vcc, 3, v156
	v_mul_f32_e32 v92, v94, v91
	v_fma_f32 v96, v212, v94, v95
	v_pk_fma_f32 v[108:109], v[194:195], v[92:93], v[108:109] op_sel_hi:[1,0,1]
	v_pk_fma_f32 v[110:111], v[196:197], v[92:93], v[110:111] op_sel_hi:[1,0,1]
	v_cndmask_b32_e32 v37, v37, v96, vcc
	v_pk_fma_f32 v[112:113], v[198:199], v[92:93], v[112:113] op_sel_hi:[1,0,1]
	v_pk_fma_f32 v[114:115], v[200:201], v[92:93], v[114:115] op_sel_hi:[1,0,1]
	v_pk_fma_f32 v[116:117], v[202:203], v[92:93], v[116:117] op_sel_hi:[1,0,1]
	v_pk_fma_f32 v[118:119], v[204:205], v[92:93], v[118:119] op_sel_hi:[1,0,1]
	v_pk_fma_f32 v[120:121], v[206:207], v[92:93], v[120:121] op_sel_hi:[1,0,1]
	v_pk_fma_f32 v[122:123], v[208:209], v[92:93], v[122:123] op_sel_hi:[1,0,1]
	v_pk_mul_f32 v[108:109], v[90:91], v[108:109] op_sel_hi:[0,1]
	v_pk_mul_f32 v[110:111], v[90:91], v[110:111] op_sel_hi:[0,1]
	v_pk_mul_f32 v[112:113], v[90:91], v[112:113] op_sel_hi:[0,1]
	v_pk_mul_f32 v[114:115], v[90:91], v[114:115] op_sel_hi:[0,1]
	v_pk_mul_f32 v[116:117], v[90:91], v[116:117] op_sel_hi:[0,1]
	v_pk_mul_f32 v[118:119], v[90:91], v[118:119] op_sel_hi:[0,1]
	v_pk_mul_f32 v[120:121], v[90:91], v[120:121] op_sel_hi:[0,1]
	v_pk_mul_f32 v[122:123], v[90:91], v[122:123] op_sel_hi:[0,1]
	ds_read_b128 v[194:197], v159 offset:5632
	ds_read_b128 v[178:181], v159 offset:5120
	ds_read_b128 v[198:201], v159 offset:5648
	ds_read_b128 v[182:185], v159 offset:5136
	ds_read_b128 v[202:205], v159 offset:5664
	ds_read_b128 v[186:189], v159 offset:5152
	ds_read_b128 v[206:209], v159 offset:5680
	s_waitcnt lgkmcnt(7)
; __device__ __forceinline__ f32x2 fma2(f32x2 a, f32x2 b, f32x2 c) { return __builtin_elementwise_fma(a, b, c); }
; __device__ __forceinline__ float sum8(float x) { x += dppf<0x141>(x); x += dppf<0x4E>(x); x += dppf<0xB1>(x); return x; }
; template <int TB> __device__ __forceinline__ void gdn_block8(f32x2 (&S)[8], const LAS float* B, int kq, int vidx, float* oo) {
;     ...
;     for (int t0 = 0; t0 < TB; t0 += SCAN_UNR) {
;         float P = 1.f, iP = 1.f;
; #pragma unroll
;         for (int tt = 0; tt < SCAN_UNR; ++tt) {
;             const int t = t0 + tt;
;             const GOps8 n = g_ld8(B, (t + 1) & 15, kq, vidx);
;             const f32x2 k[8] = PAIRS8(c.k), q[8] = PAIRS8(c.q);
;             f32x2 pk = S[0] * k[0], pq = S[0] * q[0];
; #pragma unroll
;             for (int e = 1; e < 8; ++e) { pk = fma2(S[e], k[e], pk); pq = fma2(S[e], q[e], pq); }
;             const float dk = sum8(pk.x + pk.y), dq = sum8(pq.x + pq.y);
;             P *= c.sc.x; iP *= c.sc.w;
;             const float coef = c.sc.y * (c.v - P * dk);
;             const float cs = coef * iP; const f32x2 cf2 = {cs, cs};
; #pragma unroll
;             for (int e = 0; e < 8; ++e) S[e] = fma2(k[e], cf2, S[e]);
;             const float o = P * dq + c.sc.z * coef;
;             okA = (kq == t) ? o : okA; okB = (kq + 8 == t) ? o : okB;
;             c = n;
;         }
;         const f32x2 p2 = {P, P};
; #pragma unroll
;         for (int e = 0; e < 8; ++e) S[e] = S[e] * p2;
	v_pk_mul_f32 v[86:87], v[108:109], v[64:65]
	v_pk_mul_f32 v[88:89], v[108:109], v[48:49]
	v_pk_fma_f32 v[86:87], v[110:111], v[66:67], v[86:87]
	v_pk_fma_f32 v[88:89], v[110:111], v[50:51], v[88:89]
	v_pk_fma_f32 v[86:87], v[112:113], v[68:69], v[86:87]
	v_pk_fma_f32 v[88:89], v[112:113], v[52:53], v[88:89]
	v_pk_fma_f32 v[86:87], v[114:115], v[70:71], v[86:87]
	v_pk_fma_f32 v[88:89], v[114:115], v[54:55], v[88:89]
	v_pk_fma_f32 v[86:87], v[116:117], v[72:73], v[86:87]
	v_pk_fma_f32 v[88:89], v[116:117], v[56:57], v[88:89]
	v_pk_fma_f32 v[86:87], v[118:119], v[74:75], v[86:87]
	v_pk_fma_f32 v[88:89], v[118:119], v[58:59], v[88:89]
	v_pk_fma_f32 v[86:87], v[120:121], v[76:77], v[86:87]
	v_pk_fma_f32 v[88:89], v[120:121], v[60:61], v[88:89]
	v_pk_fma_f32 v[86:87], v[122:123], v[78:79], v[86:87]
	v_pk_fma_f32 v[88:89], v[122:123], v[62:63], v[88:89]
	v_add_f32_e32 v86, v86, v87
	v_add_f32_e32 v88, v88, v89
	ds_read_b128 v[190:193], v159 offset:5168
	v_add_f32_dpp v86, v86, v86 row_half_mirror row_mask:0xf bank_mask:0xf bound_ctrl:1
	v_add_f32_dpp v88, v88, v88 row_half_mirror row_mask:0xf bank_mask:0xf bound_ctrl:1
	ds_read_b128 v[210:213], v97 offset:80
	v_add_f32_dpp v86, v86, v86 quad_perm:[2,3,0,1] row_mask:0xf bank_mask:0xf bound_ctrl:1
	v_add_f32_dpp v88, v88, v88 quad_perm:[2,3,0,1] row_mask:0xf bank_mask:0xf bound_ctrl:1
	ds_read_b32 v214, v160 offset:16704
	v_add_f32_dpp v86, v86, v86 quad_perm:[1,0,3,2] row_mask:0xf bank_mask:0xf bound_ctrl:1
	v_add_f32_dpp v88, v88, v88 quad_perm:[1,0,3,2] row_mask:0xf bank_mask:0xf bound_ctrl:1
	v_fma_f32 v94, -v80, v86, v84
	v_mul_f32_e32 v95, v80, v88
	v_mul_f32_e32 v94, v81, v94
	v_cmp_eq_u32_e32 vcc, 4, v156
	v_mul_f32_e32 v92, v94, v83
	v_fma_f32 v96, v82, v94, v95
	v_pk_fma_f32 v[108:109], v[64:65], v[92:93], v[108:109] op_sel_hi:[1,0,1]
	v_pk_fma_f32 v[110:111], v[66:67], v[92:93], v[110:111] op_sel_hi:[1,0,1]
	v_cndmask_b32_e32 v37, v37, v96, vcc
	v_pk_fma_f32 v[112:113], v[68:69], v[92:93], v[112:113] op_sel_hi:[1,0,1]
	v_pk_fma_f32 v[114:115], v[70:71], v[92:93], v[114:115] op_sel_hi:[1,0,1]
	v_pk_fma_f32 v[116:117], v[72:73], v[92:93], v[116:117] op_sel_hi:[1,0,1]
	v_pk_fma_f32 v[118:119], v[74:75], v[92:93], v[118:119] op_sel_hi:[1,0,1]
	v_pk_fma_f32 v[120:121], v[76:77], v[92:93], v[120:121] op_sel_hi:[1,0,1]
	v_pk_fma_f32 v[122:123], v[78:79], v[92:93], v[122:123] op_sel_hi:[1,0,1]
	ds_read_b128 v[64:67], v159 offset:6656
	ds_read_b128 v[48:51], v159 offset:6144
	ds_read_b128 v[68:71], v159 offset:6672
	ds_read_b128 v[52:55], v159 offset:6160
	ds_read_b128 v[72:75], v159 offset:6688
	ds_read_b128 v[56:59], v159 offset:6176
	ds_read_b128 v[76:79], v159 offset:6704
	s_waitcnt lgkmcnt(7)
	v_pk_mul_f32 v[86:87], v[108:109], v[194:195]
	v_pk_mul_f32 v[88:89], v[108:109], v[178:179]
	v_pk_fma_f32 v[86:87], v[110:111], v[196:197], v[86:87]
	v_pk_fma_f32 v[88:89], v[110:111], v[180:181], v[88:89]
	v_pk_fma_f32 v[86:87], v[112:113], v[198:199], v[86:87]
	v_pk_fma_f32 v[88:89], v[112:113], v[182:183], v[88:89]
	v_mul_f32_e32 v90, v80, v210
	v_mul_f32_e32 v91, v83, v213
	v_pk_fma_f32 v[86:87], v[114:115], v[200:201], v[86:87]
	v_pk_fma_f32 v[88:89], v[114:115], v[184:185], v[88:89]
	v_pk_fma_f32 v[86:87], v[116:117], v[202:203], v[86:87]
	v_pk_fma_f32 v[88:89], v[116:117], v[186:187], v[88:89]
	v_pk_fma_f32 v[86:87], v[118:119], v[204:205], v[86:87]
	v_pk_fma_f32 v[88:89], v[118:119], v[188:189], v[88:89]
	v_pk_fma_f32 v[86:87], v[120:121], v[206:207], v[86:87]
	v_pk_fma_f32 v[88:89], v[120:121], v[190:191], v[88:89]
	v_pk_fma_f32 v[86:87], v[122:123], v[208:209], v[86:87]
	v_pk_fma_f32 v[88:89], v[122:123], v[192:193], v[88:89]
	v_add_f32_e32 v86, v86, v87
	v_add_f32_e32 v88, v88, v89
	ds_read_b128 v[60:63], v159 offset:6192
	v_add_f32_dpp v86, v86, v86 row_half_mirror row_mask:0xf bank_mask:0xf bound_ctrl:1
	v_add_f32_dpp v88, v88, v88 row_half_mirror row_mask:0xf bank_mask:0xf bound_ctrl:1
	ds_read_b128 v[80:83], v97 offset:96
	v_add_f32_dpp v86, v86, v86 quad_perm:[2,3,0,1] row_mask:0xf bank_mask:0xf bound_ctrl:1
	v_add_f32_dpp v88, v88, v88 quad_perm:[2,3,0,1] row_mask:0xf bank_mask:0xf bound_ctrl:1
	ds_read_b32 v84, v160 offset:16768
	v_add_f32_dpp v86, v86, v86 quad_perm:[1,0,3,2] row_mask:0xf bank_mask:0xf bound_ctrl:1
	v_add_f32_dpp v88, v88, v88 quad_perm:[1,0,3,2] row_mask:0xf bank_mask:0xf bound_ctrl:1
	v_fma_f32 v94, -v90, v86, v214
	v_mul_f32_e32 v95, v90, v88
	v_mul_f32_e32 v94, v211, v94
	v_cmp_eq_u32_e32 vcc, 5, v156
	v_mul_f32_e32 v92, v94, v91
	v_fma_f32 v96, v212, v94, v95
	v_pk_fma_f32 v[108:109], v[194:195], v[92:93], v[108:109] op_sel_hi:[1,0,1]
	v_pk_fma_f32 v[110:111], v[196:197], v[92:93], v[110:111] op_sel_hi:[1,0,1]
	v_cndmask_b32_e32 v37, v37, v96, vcc
	v_pk_fma_f32 v[112:113], v[198:199], v[92:93], v[112:113] op_sel_hi:[1,0,1]
	v_pk_fma_f32 v[114:115], v[200:201], v[92:93], v[114:115] op_sel_hi:[1,0,1]
	v_pk_fma_f32 v[116:117], v[202:203], v[92:93], v[116:117] op_sel_hi:[1,0,1]
	v_pk_fma_f32 v[118:119], v[204:205], v[92:93], v[118:119] op_sel_hi:[1,0,1]
	v_pk_fma_f32 v[120:121], v[206:207], v[92:93], v[120:121] op_sel_hi:[1,0,1]
	v_pk_fma_f32 v[122:123], v[208:209], v[92:93], v[122:123] op_sel_hi:[1,0,1]
	ds_read_b128 v[194:197], v159 offset:7680
	ds_read_b128 v[178:181], v159 offset:7168
	ds_read_b128 v[198:201], v159 offset:7696
	ds_read_b128 v[182:185], v159 offset:7184
	ds_read_b128 v[202:205], v159 offset:7712
	ds_read_b128 v[186:189], v159 offset:7200
	ds_read_b128 v[206:209], v159 offset:7728
	s_waitcnt lgkmcnt(7)
; __device__ __forceinline__ f32x2 fma2(f32x2 a, f32x2 b, f32x2 c) { return __builtin_elementwise_fma(a, b, c); }
; __device__ __forceinline__ float sum8(float x) { x += dppf<0x141>(x); x += dppf<0x4E>(x); x += dppf<0xB1>(x); return x; }
; template <int TB> __device__ __forceinline__ void gdn_block8(f32x2 (&S)[8], const LAS float* B, int kq, int vidx, float* oo) {
;     ...
;     for (int t0 = 0; t0 < TB; t0 += SCAN_UNR) {
;         float P = 1.f, iP = 1.f;
; #pragma unroll
;         for (int tt = 0; tt < SCAN_UNR; ++tt) {
;             const int t = t0 + tt;
;             const GOps8 n = g_ld8(B, (t + 1) & 15, kq, vidx);
;             const f32x2 k[8] = PAIRS8(c.k), q[8] = PAIRS8(c.q);
;             f32x2 pk = S[0] * k[0], pq = S[0] * q[0];
; #pragma unroll
;             for (int e = 1; e < 8; ++e) { pk = fma2(S[e], k[e], pk); pq = fma2(S[e], q[e], pq); }
;             const float dk = sum8(pk.x + pk.y), dq = sum8(pq.x + pq.y);
;             P *= c.sc.x; iP *= c.sc.w;
;             const float coef = c.sc.y * (c.v - P * dk);
;             const float cs = coef * iP; const f32x2 cf2 = {cs, cs};
; #pragma unroll
;             for (int e = 0; e < 8; ++e) S[e] = fma2(k[e], cf2, S[e]);
;             const float o = P * dq + c.sc.z * coef;
;             okA = (kq == t) ? o : okA; okB = (kq + 8 == t) ? o : okB;
;             c = n;
;         }
;         const f32x2 p2 = {P, P};
; #pragma unroll
;         for (int e = 0; e < 8; ++e) S[e] = S[e] * p2;
	v_pk_mul_f32 v[86:87], v[108:109], v[64:65]
	v_pk_mul_f32 v[88:89], v[108:109], v[48:49]
	v_pk_fma_f32 v[86:87], v[110:111], v[66:67], v[86:87]
	v_pk_fma_f32 v[88:89], v[110:111], v[50:51], v[88:89]
	v_pk_fma_f32 v[86:87], v[112:113], v[68:69], v[86:87]
	v_pk_fma_f32 v[88:89], v[112:113], v[52:53], v[88:89]
	v_mul_f32_e32 v90, v90, v80
	v_mul_f32_e32 v91, v91, v83
	v_pk_fma_f32 v[86:87], v[114:115], v[70:71], v[86:87]
	v_pk_fma_f32 v[88:89], v[114:115], v[54:55], v[88:89]
	v_pk_fma_f32 v[86:87], v[116:117], v[72:73], v[86:87]
	v_pk_fma_f32 v[88:89], v[116:117], v[56:57], v[88:89]
	v_pk_fma_f32 v[86:87], v[118:119], v[74:75], v[86:87]
	v_pk_fma_f32 v[88:89], v[118:119], v[58:59], v[88:89]
	v_pk_fma_f32 v[86:87], v[120:121], v[76:77], v[86:87]
	v_pk_fma_f32 v[88:89], v[120:121], v[60:61], v[88:89]
	v_pk_fma_f32 v[86:87], v[122:123], v[78:79], v[86:87]
	v_pk_fma_f32 v[88:89], v[122:123], v[62:63], v[88:89]
	v_add_f32_e32 v86, v86, v87
	v_add_f32_e32 v88, v88, v89
	ds_read_b128 v[190:193], v159 offset:7216
	v_add_f32_dpp v86, v86, v86 row_half_mirror row_mask:0xf bank_mask:0xf bound_ctrl:1
	v_add_f32_dpp v88, v88, v88 row_half_mirror row_mask:0xf bank_mask:0xf bound_ctrl:1
	ds_read_b128 v[210:213], v97 offset:112
	v_add_f32_dpp v86, v86, v86 quad_perm:[2,3,0,1] row_mask:0xf bank_mask:0xf bound_ctrl:1
	v_add_f32_dpp v88, v88, v88 quad_perm:[2,3,0,1] row_mask:0xf bank_mask:0xf bound_ctrl:1
	ds_read_b32 v214, v160 offset:16832
	v_add_f32_dpp v86, v86, v86 quad_perm:[1,0,3,2] row_mask:0xf bank_mask:0xf bound_ctrl:1
	v_add_f32_dpp v88, v88, v88 quad_perm:[1,0,3,2] row_mask:0xf bank_mask:0xf bound_ctrl:1
	v_fma_f32 v94, -v90, v86, v84
	v_mul_f32_e32 v95, v90, v88
	v_mul_f32_e32 v94, v81, v94
	v_cmp_eq_u32_e32 vcc, 6, v156
	v_mul_f32_e32 v92, v94, v91
	v_fma_f32 v96, v82, v94, v95
	v_pk_fma_f32 v[108:109], v[64:65], v[92:93], v[108:109] op_sel_hi:[1,0,1]
	v_pk_fma_f32 v[110:111], v[66:67], v[92:93], v[110:111] op_sel_hi:[1,0,1]
	v_cndmask_b32_e32 v37, v37, v96, vcc
	v_pk_fma_f32 v[112:113], v[68:69], v[92:93], v[112:113] op_sel_hi:[1,0,1]
	v_pk_fma_f32 v[114:115], v[70:71], v[92:93], v[114:115] op_sel_hi:[1,0,1]
	v_pk_fma_f32 v[116:117], v[72:73], v[92:93], v[116:117] op_sel_hi:[1,0,1]
	v_pk_fma_f32 v[118:119], v[74:75], v[92:93], v[118:119] op_sel_hi:[1,0,1]
	v_pk_fma_f32 v[120:121], v[76:77], v[92:93], v[120:121] op_sel_hi:[1,0,1]
	v_pk_fma_f32 v[122:123], v[78:79], v[92:93], v[122:123] op_sel_hi:[1,0,1]
	ds_read_b128 v[64:67], v159 offset:8704
	ds_read_b128 v[48:51], v159 offset:8192
	ds_read_b128 v[68:71], v159 offset:8720
	ds_read_b128 v[52:55], v159 offset:8208
	ds_read_b128 v[72:75], v159 offset:8736
	ds_read_b128 v[56:59], v159 offset:8224
	ds_read_b128 v[76:79], v159 offset:8752
	s_waitcnt lgkmcnt(7)
	v_pk_mul_f32 v[86:87], v[108:109], v[194:195]
	v_pk_mul_f32 v[88:89], v[108:109], v[178:179]
	v_pk_fma_f32 v[86:87], v[110:111], v[196:197], v[86:87]
	v_pk_fma_f32 v[88:89], v[110:111], v[180:181], v[88:89]
	v_pk_fma_f32 v[86:87], v[112:113], v[198:199], v[86:87]
	v_pk_fma_f32 v[88:89], v[112:113], v[182:183], v[88:89]
	v_mul_f32_e32 v90, v90, v210
	v_mul_f32_e32 v91, v91, v213
	v_pk_fma_f32 v[86:87], v[114:115], v[200:201], v[86:87]
	v_pk_fma_f32 v[88:89], v[114:115], v[184:185], v[88:89]
	v_pk_fma_f32 v[86:87], v[116:117], v[202:203], v[86:87]
	v_pk_fma_f32 v[88:89], v[116:117], v[186:187], v[88:89]
	v_pk_fma_f32 v[86:87], v[118:119], v[204:205], v[86:87]
	v_pk_fma_f32 v[88:89], v[118:119], v[188:189], v[88:89]
	v_pk_fma_f32 v[86:87], v[120:121], v[206:207], v[86:87]
	v_pk_fma_f32 v[88:89], v[120:121], v[190:191], v[88:89]
	v_pk_fma_f32 v[86:87], v[122:123], v[208:209], v[86:87]
	v_pk_fma_f32 v[88:89], v[122:123], v[192:193], v[88:89]
	v_add_f32_e32 v86, v86, v87
	v_add_f32_e32 v88, v88, v89
	ds_read_b128 v[60:63], v159 offset:8240
	v_add_f32_dpp v86, v86, v86 row_half_mirror row_mask:0xf bank_mask:0xf bound_ctrl:1
	v_add_f32_dpp v88, v88, v88 row_half_mirror row_mask:0xf bank_mask:0xf bound_ctrl:1
	ds_read_b128 v[80:83], v97 offset:128
	v_add_f32_dpp v86, v86, v86 quad_perm:[2,3,0,1] row_mask:0xf bank_mask:0xf bound_ctrl:1
	v_add_f32_dpp v88, v88, v88 quad_perm:[2,3,0,1] row_mask:0xf bank_mask:0xf bound_ctrl:1
	ds_read_b32 v84, v160 offset:16896
	v_add_f32_dpp v86, v86, v86 quad_perm:[1,0,3,2] row_mask:0xf bank_mask:0xf bound_ctrl:1
	v_add_f32_dpp v88, v88, v88 quad_perm:[1,0,3,2] row_mask:0xf bank_mask:0xf bound_ctrl:1
	v_fma_f32 v94, -v90, v86, v214
	v_mul_f32_e32 v95, v90, v88
	v_mul_f32_e32 v94, v211, v94
	v_cmp_eq_u32_e32 vcc, 7, v156
	v_mul_f32_e32 v92, v94, v91
	v_fma_f32 v96, v212, v94, v95
	v_pk_fma_f32 v[108:109], v[194:195], v[92:93], v[108:109] op_sel_hi:[1,0,1]
	v_pk_fma_f32 v[110:111], v[196:197], v[92:93], v[110:111] op_sel_hi:[1,0,1]
	v_cndmask_b32_e32 v37, v37, v96, vcc
	v_pk_fma_f32 v[112:113], v[198:199], v[92:93], v[112:113] op_sel_hi:[1,0,1]
	v_pk_fma_f32 v[114:115], v[200:201], v[92:93], v[114:115] op_sel_hi:[1,0,1]
	v_pk_fma_f32 v[116:117], v[202:203], v[92:93], v[116:117] op_sel_hi:[1,0,1]
	v_pk_fma_f32 v[118:119], v[204:205], v[92:93], v[118:119] op_sel_hi:[1,0,1]
	v_pk_fma_f32 v[120:121], v[206:207], v[92:93], v[120:121] op_sel_hi:[1,0,1]
	v_pk_fma_f32 v[122:123], v[208:209], v[92:93], v[122:123] op_sel_hi:[1,0,1]
	v_pk_mul_f32 v[108:109], v[90:91], v[108:109] op_sel_hi:[0,1]
	v_pk_mul_f32 v[110:111], v[90:91], v[110:111] op_sel_hi:[0,1]
	v_pk_mul_f32 v[112:113], v[90:91], v[112:113] op_sel_hi:[0,1]
	v_pk_mul_f32 v[114:115], v[90:91], v[114:115] op_sel_hi:[0,1]
	v_pk_mul_f32 v[116:117], v[90:91], v[116:117] op_sel_hi:[0,1]
	v_pk_mul_f32 v[118:119], v[90:91], v[118:119] op_sel_hi:[0,1]
	v_pk_mul_f32 v[120:121], v[90:91], v[120:121] op_sel_hi:[0,1]
	v_pk_mul_f32 v[122:123], v[90:91], v[122:123] op_sel_hi:[0,1]
	ds_read_b128 v[194:197], v159 offset:9728
	ds_read_b128 v[178:181], v159 offset:9216
	ds_read_b128 v[198:201], v159 offset:9744
	ds_read_b128 v[182:185], v159 offset:9232
	ds_read_b128 v[202:205], v159 offset:9760
	ds_read_b128 v[186:189], v159 offset:9248
	ds_read_b128 v[206:209], v159 offset:9776
	s_waitcnt lgkmcnt(7)
; __device__ __forceinline__ f32x2 fma2(f32x2 a, f32x2 b, f32x2 c) { return __builtin_elementwise_fma(a, b, c); }
; __device__ __forceinline__ float sum8(float x) { x += dppf<0x141>(x); x += dppf<0x4E>(x); x += dppf<0xB1>(x); return x; }
; template <int TB> __device__ __forceinline__ void gdn_block8(f32x2 (&S)[8], const LAS float* B, int kq, int vidx, float* oo) {
;     ...
;     for (int t0 = 0; t0 < TB; t0 += SCAN_UNR) {
;         float P = 1.f, iP = 1.f;
; #pragma unroll
;         for (int tt = 0; tt < SCAN_UNR; ++tt) {
;             const int t = t0 + tt;
;             const GOps8 n = g_ld8(B, (t + 1) & 15, kq, vidx);
;             const f32x2 k[8] = PAIRS8(c.k), q[8] = PAIRS8(c.q);
;             f32x2 pk = S[0] * k[0], pq = S[0] * q[0];
; #pragma unroll
;             for (int e = 1; e < 8; ++e) { pk = fma2(S[e], k[e], pk); pq = fma2(S[e], q[e], pq); }
;             const float dk = sum8(pk.x + pk.y), dq = sum8(pq.x + pq.y);
;             P *= c.sc.x; iP *= c.sc.w;
;             const float coef = c.sc.y * (c.v - P * dk);
;             const float cs = coef * iP; const f32x2 cf2 = {cs, cs};
; #pragma unroll
;             for (int e = 0; e < 8; ++e) S[e] = fma2(k[e], cf2, S[e]);
;             const float o = P * dq + c.sc.z * coef;
;             okA = (kq == t) ? o : okA; okB = (kq + 8 == t) ? o : okB;
;             c = n;
;         }
;         const f32x2 p2 = {P, P};
; #pragma unroll
;         for (int e = 0; e < 8; ++e) S[e] = S[e] * p2;
	v_pk_mul_f32 v[86:87], v[108:109], v[64:65]
	v_pk_mul_f32 v[88:89], v[108:109], v[48:49]
	v_pk_fma_f32 v[86:87], v[110:111], v[66:67], v[86:87]
	v_pk_fma_f32 v[88:89], v[110:111], v[50:51], v[88:89]
	v_pk_fma_f32 v[86:87], v[112:113], v[68:69], v[86:87]
	v_pk_fma_f32 v[88:89], v[112:113], v[52:53], v[88:89]
	v_pk_fma_f32 v[86:87], v[114:115], v[70:71], v[86:87]
	v_pk_fma_f32 v[88:89], v[114:115], v[54:55], v[88:89]
	v_pk_fma_f32 v[86:87], v[116:117], v[72:73], v[86:87]
	v_pk_fma_f32 v[88:89], v[116:117], v[56:57], v[88:89]
	v_pk_fma_f32 v[86:87], v[118:119], v[74:75], v[86:87]
	v_pk_fma_f32 v[88:89], v[118:119], v[58:59], v[88:89]
	v_pk_fma_f32 v[86:87], v[120:121], v[76:77], v[86:87]
	v_pk_fma_f32 v[88:89], v[120:121], v[60:61], v[88:89]
	v_pk_fma_f32 v[86:87], v[122:123], v[78:79], v[86:87]
	v_pk_fma_f32 v[88:89], v[122:123], v[62:63], v[88:89]
	v_add_f32_e32 v86, v86, v87
	v_add_f32_e32 v88, v88, v89
	ds_read_b128 v[190:193], v159 offset:9264
	v_add_f32_dpp v86, v86, v86 row_half_mirror row_mask:0xf bank_mask:0xf bound_ctrl:1
	v_add_f32_dpp v88, v88, v88 row_half_mirror row_mask:0xf bank_mask:0xf bound_ctrl:1
	ds_read_b128 v[210:213], v97 offset:144
	v_add_f32_dpp v86, v86, v86 quad_perm:[2,3,0,1] row_mask:0xf bank_mask:0xf bound_ctrl:1
	v_add_f32_dpp v88, v88, v88 quad_perm:[2,3,0,1] row_mask:0xf bank_mask:0xf bound_ctrl:1
	ds_read_b32 v214, v160 offset:16960
	v_add_f32_dpp v86, v86, v86 quad_perm:[1,0,3,2] row_mask:0xf bank_mask:0xf bound_ctrl:1
	v_add_f32_dpp v88, v88, v88 quad_perm:[1,0,3,2] row_mask:0xf bank_mask:0xf bound_ctrl:1
	v_fma_f32 v94, -v80, v86, v84
	v_mul_f32_e32 v95, v80, v88
	v_mul_f32_e32 v94, v81, v94
	v_cmp_eq_u32_e32 vcc, 0, v156
	v_mul_f32_e32 v92, v94, v83
	v_fma_f32 v96, v82, v94, v95
	v_pk_fma_f32 v[108:109], v[64:65], v[92:93], v[108:109] op_sel_hi:[1,0,1]
	v_pk_fma_f32 v[110:111], v[66:67], v[92:93], v[110:111] op_sel_hi:[1,0,1]
	v_cndmask_b32_e32 v36, v36, v96, vcc
	v_pk_fma_f32 v[112:113], v[68:69], v[92:93], v[112:113] op_sel_hi:[1,0,1]
	v_pk_fma_f32 v[114:115], v[70:71], v[92:93], v[114:115] op_sel_hi:[1,0,1]
	v_pk_fma_f32 v[116:117], v[72:73], v[92:93], v[116:117] op_sel_hi:[1,0,1]
	v_pk_fma_f32 v[118:119], v[74:75], v[92:93], v[118:119] op_sel_hi:[1,0,1]
	v_pk_fma_f32 v[120:121], v[76:77], v[92:93], v[120:121] op_sel_hi:[1,0,1]
	v_pk_fma_f32 v[122:123], v[78:79], v[92:93], v[122:123] op_sel_hi:[1,0,1]
	ds_read_b128 v[64:67], v159 offset:10752
	ds_read_b128 v[48:51], v159 offset:10240
	ds_read_b128 v[68:71], v159 offset:10768
	ds_read_b128 v[52:55], v159 offset:10256
	ds_read_b128 v[72:75], v159 offset:10784
	ds_read_b128 v[56:59], v159 offset:10272
	ds_read_b128 v[76:79], v159 offset:10800
	s_waitcnt lgkmcnt(7)
	v_pk_mul_f32 v[86:87], v[108:109], v[194:195]
	v_pk_mul_f32 v[88:89], v[108:109], v[178:179]
	v_pk_fma_f32 v[86:87], v[110:111], v[196:197], v[86:87]
	v_pk_fma_f32 v[88:89], v[110:111], v[180:181], v[88:89]
	v_pk_fma_f32 v[86:87], v[112:113], v[198:199], v[86:87]
	v_pk_fma_f32 v[88:89], v[112:113], v[182:183], v[88:89]
	v_mul_f32_e32 v90, v80, v210
	v_mul_f32_e32 v91, v83, v213
	v_pk_fma_f32 v[86:87], v[114:115], v[200:201], v[86:87]
	v_pk_fma_f32 v[88:89], v[114:115], v[184:185], v[88:89]
	v_pk_fma_f32 v[86:87], v[116:117], v[202:203], v[86:87]
	v_pk_fma_f32 v[88:89], v[116:117], v[186:187], v[88:89]
	v_pk_fma_f32 v[86:87], v[118:119], v[204:205], v[86:87]
	v_pk_fma_f32 v[88:89], v[118:119], v[188:189], v[88:89]
	v_pk_fma_f32 v[86:87], v[120:121], v[206:207], v[86:87]
	v_pk_fma_f32 v[88:89], v[120:121], v[190:191], v[88:89]
	v_pk_fma_f32 v[86:87], v[122:123], v[208:209], v[86:87]
	v_pk_fma_f32 v[88:89], v[122:123], v[192:193], v[88:89]
	v_add_f32_e32 v86, v86, v87
	v_add_f32_e32 v88, v88, v89
	ds_read_b128 v[60:63], v159 offset:10288
	v_add_f32_dpp v86, v86, v86 row_half_mirror row_mask:0xf bank_mask:0xf bound_ctrl:1
	v_add_f32_dpp v88, v88, v88 row_half_mirror row_mask:0xf bank_mask:0xf bound_ctrl:1
	ds_read_b128 v[80:83], v97 offset:160
	v_add_f32_dpp v86, v86, v86 quad_perm:[2,3,0,1] row_mask:0xf bank_mask:0xf bound_ctrl:1
	v_add_f32_dpp v88, v88, v88 quad_perm:[2,3,0,1] row_mask:0xf bank_mask:0xf bound_ctrl:1
	ds_read_b32 v84, v160 offset:17024
	v_add_f32_dpp v86, v86, v86 quad_perm:[1,0,3,2] row_mask:0xf bank_mask:0xf bound_ctrl:1
	v_add_f32_dpp v88, v88, v88 quad_perm:[1,0,3,2] row_mask:0xf bank_mask:0xf bound_ctrl:1
	v_fma_f32 v94, -v90, v86, v214
	v_mul_f32_e32 v95, v90, v88
	v_mul_f32_e32 v94, v211, v94
	v_cmp_eq_u32_e32 vcc, 1, v156
	v_mul_f32_e32 v92, v94, v91
	v_fma_f32 v96, v212, v94, v95
	v_pk_fma_f32 v[108:109], v[194:195], v[92:93], v[108:109] op_sel_hi:[1,0,1]
	v_pk_fma_f32 v[110:111], v[196:197], v[92:93], v[110:111] op_sel_hi:[1,0,1]
	v_cndmask_b32_e32 v36, v36, v96, vcc
	v_pk_fma_f32 v[112:113], v[198:199], v[92:93], v[112:113] op_sel_hi:[1,0,1]
	v_pk_fma_f32 v[114:115], v[200:201], v[92:93], v[114:115] op_sel_hi:[1,0,1]
	v_pk_fma_f32 v[116:117], v[202:203], v[92:93], v[116:117] op_sel_hi:[1,0,1]
	v_pk_fma_f32 v[118:119], v[204:205], v[92:93], v[118:119] op_sel_hi:[1,0,1]
	v_pk_fma_f32 v[120:121], v[206:207], v[92:93], v[120:121] op_sel_hi:[1,0,1]
	v_pk_fma_f32 v[122:123], v[208:209], v[92:93], v[122:123] op_sel_hi:[1,0,1]
	ds_read_b128 v[194:197], v159 offset:11776
	ds_read_b128 v[178:181], v159 offset:11264
	ds_read_b128 v[198:201], v159 offset:11792
	ds_read_b128 v[182:185], v159 offset:11280
	ds_read_b128 v[202:205], v159 offset:11808
	ds_read_b128 v[186:189], v159 offset:11296
	ds_read_b128 v[206:209], v159 offset:11824
	s_waitcnt lgkmcnt(7)
; __device__ __forceinline__ f32x2 fma2(f32x2 a, f32x2 b, f32x2 c) { return __builtin_elementwise_fma(a, b, c); }
; __device__ __forceinline__ float sum8(float x) { x += dppf<0x141>(x); x += dppf<0x4E>(x); x += dppf<0xB1>(x); return x; }
; template <int TB> __device__ __forceinline__ void gdn_block8(f32x2 (&S)[8], const LAS float* B, int kq, int vidx, float* oo) {
;     ...
;     for (int t0 = 0; t0 < TB; t0 += SCAN_UNR) {
;         float P = 1.f, iP = 1.f;
; #pragma unroll
;         for (int tt = 0; tt < SCAN_UNR; ++tt) {
;             const int t = t0 + tt;
;             const GOps8 n = g_ld8(B, (t + 1) & 15, kq, vidx);
;             const f32x2 k[8] = PAIRS8(c.k), q[8] = PAIRS8(c.q);
;             f32x2 pk = S[0] * k[0], pq = S[0] * q[0];
; #pragma unroll
;             for (int e = 1; e < 8; ++e) { pk = fma2(S[e], k[e], pk); pq = fma2(S[e], q[e], pq); }
;             const float dk = sum8(pk.x + pk.y), dq = sum8(pq.x + pq.y);
;             P *= c.sc.x; iP *= c.sc.w;
;             const float coef = c.sc.y * (c.v - P * dk);
;             const float cs = coef * iP; const f32x2 cf2 = {cs, cs};
; #pragma unroll
;             for (int e = 0; e < 8; ++e) S[e] = fma2(k[e], cf2, S[e]);
;             const float o = P * dq + c.sc.z * coef;
;             okA = (kq == t) ? o : okA; okB = (kq + 8 == t) ? o : okB;
;             c = n;
;         }
;         const f32x2 p2 = {P, P};
; #pragma unroll
;         for (int e = 0; e < 8; ++e) S[e] = S[e] * p2;
	v_pk_mul_f32 v[86:87], v[108:109], v[64:65]
	v_pk_mul_f32 v[88:89], v[108:109], v[48:49]
	v_pk_fma_f32 v[86:87], v[110:111], v[66:67], v[86:87]
	v_pk_fma_f32 v[88:89], v[110:111], v[50:51], v[88:89]
	v_pk_fma_f32 v[86:87], v[112:113], v[68:69], v[86:87]
	v_pk_fma_f32 v[88:89], v[112:113], v[52:53], v[88:89]
	v_mul_f32_e32 v90, v90, v80
	v_mul_f32_e32 v91, v91, v83
	v_pk_fma_f32 v[86:87], v[114:115], v[70:71], v[86:87]
	v_pk_fma_f32 v[88:89], v[114:115], v[54:55], v[88:89]
	v_pk_fma_f32 v[86:87], v[116:117], v[72:73], v[86:87]
	v_pk_fma_f32 v[88:89], v[116:117], v[56:57], v[88:89]
	v_pk_fma_f32 v[86:87], v[118:119], v[74:75], v[86:87]
	v_pk_fma_f32 v[88:89], v[118:119], v[58:59], v[88:89]
	v_pk_fma_f32 v[86:87], v[120:121], v[76:77], v[86:87]
	v_pk_fma_f32 v[88:89], v[120:121], v[60:61], v[88:89]
	v_pk_fma_f32 v[86:87], v[122:123], v[78:79], v[86:87]
	v_pk_fma_f32 v[88:89], v[122:123], v[62:63], v[88:89]
	v_add_f32_e32 v86, v86, v87
	v_add_f32_e32 v88, v88, v89
	ds_read_b128 v[190:193], v159 offset:11312
	v_add_f32_dpp v86, v86, v86 row_half_mirror row_mask:0xf bank_mask:0xf bound_ctrl:1
	v_add_f32_dpp v88, v88, v88 row_half_mirror row_mask:0xf bank_mask:0xf bound_ctrl:1
	ds_read_b128 v[210:213], v97 offset:176
	v_add_f32_dpp v86, v86, v86 quad_perm:[2,3,0,1] row_mask:0xf bank_mask:0xf bound_ctrl:1
	v_add_f32_dpp v88, v88, v88 quad_perm:[2,3,0,1] row_mask:0xf bank_mask:0xf bound_ctrl:1
	ds_read_b32 v214, v160 offset:17088
	v_add_f32_dpp v86, v86, v86 quad_perm:[1,0,3,2] row_mask:0xf bank_mask:0xf bound_ctrl:1
	v_add_f32_dpp v88, v88, v88 quad_perm:[1,0,3,2] row_mask:0xf bank_mask:0xf bound_ctrl:1
	v_fma_f32 v94, -v90, v86, v84
	v_mul_f32_e32 v95, v90, v88
	v_mul_f32_e32 v94, v81, v94
	v_cmp_eq_u32_e32 vcc, 2, v156
	v_mul_f32_e32 v92, v94, v91
	v_fma_f32 v96, v82, v94, v95
	v_pk_fma_f32 v[108:109], v[64:65], v[92:93], v[108:109] op_sel_hi:[1,0,1]
	v_pk_fma_f32 v[110:111], v[66:67], v[92:93], v[110:111] op_sel_hi:[1,0,1]
	v_cndmask_b32_e32 v36, v36, v96, vcc
	v_pk_fma_f32 v[112:113], v[68:69], v[92:93], v[112:113] op_sel_hi:[1,0,1]
	v_pk_fma_f32 v[114:115], v[70:71], v[92:93], v[114:115] op_sel_hi:[1,0,1]
	v_pk_fma_f32 v[116:117], v[72:73], v[92:93], v[116:117] op_sel_hi:[1,0,1]
	v_pk_fma_f32 v[118:119], v[74:75], v[92:93], v[118:119] op_sel_hi:[1,0,1]
	v_pk_fma_f32 v[120:121], v[76:77], v[92:93], v[120:121] op_sel_hi:[1,0,1]
	v_pk_fma_f32 v[122:123], v[78:79], v[92:93], v[122:123] op_sel_hi:[1,0,1]
	ds_read_b128 v[64:67], v159 offset:12800
	ds_read_b128 v[48:51], v159 offset:12288
	ds_read_b128 v[68:71], v159 offset:12816
	ds_read_b128 v[52:55], v159 offset:12304
	ds_read_b128 v[72:75], v159 offset:12832
	ds_read_b128 v[56:59], v159 offset:12320
	ds_read_b128 v[76:79], v159 offset:12848
	s_waitcnt lgkmcnt(7)
	v_pk_mul_f32 v[86:87], v[108:109], v[194:195]
	v_pk_mul_f32 v[88:89], v[108:109], v[178:179]
	v_pk_fma_f32 v[86:87], v[110:111], v[196:197], v[86:87]
	v_pk_fma_f32 v[88:89], v[110:111], v[180:181], v[88:89]
	v_pk_fma_f32 v[86:87], v[112:113], v[198:199], v[86:87]
	v_pk_fma_f32 v[88:89], v[112:113], v[182:183], v[88:89]
	v_mul_f32_e32 v90, v90, v210
	v_mul_f32_e32 v91, v91, v213
	v_pk_fma_f32 v[86:87], v[114:115], v[200:201], v[86:87]
	v_pk_fma_f32 v[88:89], v[114:115], v[184:185], v[88:89]
	v_pk_fma_f32 v[86:87], v[116:117], v[202:203], v[86:87]
	v_pk_fma_f32 v[88:89], v[116:117], v[186:187], v[88:89]
	v_pk_fma_f32 v[86:87], v[118:119], v[204:205], v[86:87]
	v_pk_fma_f32 v[88:89], v[118:119], v[188:189], v[88:89]
	v_pk_fma_f32 v[86:87], v[120:121], v[206:207], v[86:87]
	v_pk_fma_f32 v[88:89], v[120:121], v[190:191], v[88:89]
	v_pk_fma_f32 v[86:87], v[122:123], v[208:209], v[86:87]
	v_pk_fma_f32 v[88:89], v[122:123], v[192:193], v[88:89]
	v_add_f32_e32 v86, v86, v87
	v_add_f32_e32 v88, v88, v89
	ds_read_b128 v[60:63], v159 offset:12336
	v_add_f32_dpp v86, v86, v86 row_half_mirror row_mask:0xf bank_mask:0xf bound_ctrl:1
	v_add_f32_dpp v88, v88, v88 row_half_mirror row_mask:0xf bank_mask:0xf bound_ctrl:1
	ds_read_b128 v[80:83], v97 offset:192
	v_add_f32_dpp v86, v86, v86 quad_perm:[2,3,0,1] row_mask:0xf bank_mask:0xf bound_ctrl:1
	v_add_f32_dpp v88, v88, v88 quad_perm:[2,3,0,1] row_mask:0xf bank_mask:0xf bound_ctrl:1
	ds_read_b32 v84, v160 offset:17152
	v_add_f32_dpp v86, v86, v86 quad_perm:[1,0,3,2] row_mask:0xf bank_mask:0xf bound_ctrl:1
	v_add_f32_dpp v88, v88, v88 quad_perm:[1,0,3,2] row_mask:0xf bank_mask:0xf bound_ctrl:1
	v_fma_f32 v94, -v90, v86, v214
	v_mul_f32_e32 v95, v90, v88
	v_mul_f32_e32 v94, v211, v94
	v_cmp_eq_u32_e32 vcc, 3, v156
	v_mul_f32_e32 v92, v94, v91
	v_fma_f32 v96, v212, v94, v95
	v_pk_fma_f32 v[108:109], v[194:195], v[92:93], v[108:109] op_sel_hi:[1,0,1]
	v_pk_fma_f32 v[110:111], v[196:197], v[92:93], v[110:111] op_sel_hi:[1,0,1]
	v_cndmask_b32_e32 v36, v36, v96, vcc
	v_pk_fma_f32 v[112:113], v[198:199], v[92:93], v[112:113] op_sel_hi:[1,0,1]
	v_pk_fma_f32 v[114:115], v[200:201], v[92:93], v[114:115] op_sel_hi:[1,0,1]
	v_pk_fma_f32 v[116:117], v[202:203], v[92:93], v[116:117] op_sel_hi:[1,0,1]
	v_pk_fma_f32 v[118:119], v[204:205], v[92:93], v[118:119] op_sel_hi:[1,0,1]
	v_pk_fma_f32 v[120:121], v[206:207], v[92:93], v[120:121] op_sel_hi:[1,0,1]
	v_pk_fma_f32 v[122:123], v[208:209], v[92:93], v[122:123] op_sel_hi:[1,0,1]
	v_pk_mul_f32 v[108:109], v[90:91], v[108:109] op_sel_hi:[0,1]
	v_pk_mul_f32 v[110:111], v[90:91], v[110:111] op_sel_hi:[0,1]
	v_pk_mul_f32 v[112:113], v[90:91], v[112:113] op_sel_hi:[0,1]
	v_pk_mul_f32 v[114:115], v[90:91], v[114:115] op_sel_hi:[0,1]
	v_pk_mul_f32 v[116:117], v[90:91], v[116:117] op_sel_hi:[0,1]
	v_pk_mul_f32 v[118:119], v[90:91], v[118:119] op_sel_hi:[0,1]
	v_pk_mul_f32 v[120:121], v[90:91], v[120:121] op_sel_hi:[0,1]
	v_pk_mul_f32 v[122:123], v[90:91], v[122:123] op_sel_hi:[0,1]
	ds_read_b128 v[194:197], v159 offset:13824
	ds_read_b128 v[178:181], v159 offset:13312
	ds_read_b128 v[198:201], v159 offset:13840
	ds_read_b128 v[182:185], v159 offset:13328
	ds_read_b128 v[202:205], v159 offset:13856
	ds_read_b128 v[186:189], v159 offset:13344
	ds_read_b128 v[206:209], v159 offset:13872
	s_waitcnt lgkmcnt(7)
; __device__ __forceinline__ f32x2 fma2(f32x2 a, f32x2 b, f32x2 c) { return __builtin_elementwise_fma(a, b, c); }
; __device__ __forceinline__ float sum8(float x) { x += dppf<0x141>(x); x += dppf<0x4E>(x); x += dppf<0xB1>(x); return x; }
; template <int TB> __device__ __forceinline__ void gdn_block8(f32x2 (&S)[8], const LAS float* B, int kq, int vidx, float* oo) {
;     ...
;     for (int t0 = 0; t0 < TB; t0 += SCAN_UNR) {
;         float P = 1.f, iP = 1.f;
; #pragma unroll
;         for (int tt = 0; tt < SCAN_UNR; ++tt) {
;             const int t = t0 + tt;
;             const GOps8 n = g_ld8(B, (t + 1) & 15, kq, vidx);
;             const f32x2 k[8] = PAIRS8(c.k), q[8] = PAIRS8(c.q);
;             f32x2 pk = S[0] * k[0], pq = S[0] * q[0];
; #pragma unroll
;             for (int e = 1; e < 8; ++e) { pk = fma2(S[e], k[e], pk); pq = fma2(S[e], q[e], pq); }
;             const float dk = sum8(pk.x + pk.y), dq = sum8(pq.x + pq.y);
;             P *= c.sc.x; iP *= c.sc.w;
;             const float coef = c.sc.y * (c.v - P * dk);
;             const float cs = coef * iP; const f32x2 cf2 = {cs, cs};
; #pragma unroll
;             for (int e = 0; e < 8; ++e) S[e] = fma2(k[e], cf2, S[e]);
;             const float o = P * dq + c.sc.z * coef;
;             okA = (kq == t) ? o : okA; okB = (kq + 8 == t) ? o : okB;
;             c = n;
;         }
;         const f32x2 p2 = {P, P};
; #pragma unroll
;         for (int e = 0; e < 8; ++e) S[e] = S[e] * p2;
	v_pk_mul_f32 v[86:87], v[108:109], v[64:65]
	v_pk_mul_f32 v[88:89], v[108:109], v[48:49]
	v_pk_fma_f32 v[86:87], v[110:111], v[66:67], v[86:87]
	v_pk_fma_f32 v[88:89], v[110:111], v[50:51], v[88:89]
	v_pk_fma_f32 v[86:87], v[112:113], v[68:69], v[86:87]
	v_pk_fma_f32 v[88:89], v[112:113], v[52:53], v[88:89]
	v_pk_fma_f32 v[86:87], v[114:115], v[70:71], v[86:87]
	v_pk_fma_f32 v[88:89], v[114:115], v[54:55], v[88:89]
	v_pk_fma_f32 v[86:87], v[116:117], v[72:73], v[86:87]
	v_pk_fma_f32 v[88:89], v[116:117], v[56:57], v[88:89]
	v_pk_fma_f32 v[86:87], v[118:119], v[74:75], v[86:87]
	v_pk_fma_f32 v[88:89], v[118:119], v[58:59], v[88:89]
	v_pk_fma_f32 v[86:87], v[120:121], v[76:77], v[86:87]
	v_pk_fma_f32 v[88:89], v[120:121], v[60:61], v[88:89]
	v_pk_fma_f32 v[86:87], v[122:123], v[78:79], v[86:87]
	v_pk_fma_f32 v[88:89], v[122:123], v[62:63], v[88:89]
	v_add_f32_e32 v86, v86, v87
	v_add_f32_e32 v88, v88, v89
	ds_read_b128 v[190:193], v159 offset:13360
	v_add_f32_dpp v86, v86, v86 row_half_mirror row_mask:0xf bank_mask:0xf bound_ctrl:1
	v_add_f32_dpp v88, v88, v88 row_half_mirror row_mask:0xf bank_mask:0xf bound_ctrl:1
	ds_read_b128 v[210:213], v97 offset:208
	v_add_f32_dpp v86, v86, v86 quad_perm:[2,3,0,1] row_mask:0xf bank_mask:0xf bound_ctrl:1
	v_add_f32_dpp v88, v88, v88 quad_perm:[2,3,0,1] row_mask:0xf bank_mask:0xf bound_ctrl:1
	ds_read_b32 v214, v160 offset:17216
	v_add_f32_dpp v86, v86, v86 quad_perm:[1,0,3,2] row_mask:0xf bank_mask:0xf bound_ctrl:1
	v_add_f32_dpp v88, v88, v88 quad_perm:[1,0,3,2] row_mask:0xf bank_mask:0xf bound_ctrl:1
	v_fma_f32 v94, -v80, v86, v84
	v_mul_f32_e32 v95, v80, v88
	v_mul_f32_e32 v94, v81, v94
	v_cmp_eq_u32_e32 vcc, 4, v156
	v_mul_f32_e32 v92, v94, v83
	v_fma_f32 v96, v82, v94, v95
	v_pk_fma_f32 v[108:109], v[64:65], v[92:93], v[108:109] op_sel_hi:[1,0,1]
	v_pk_fma_f32 v[110:111], v[66:67], v[92:93], v[110:111] op_sel_hi:[1,0,1]
	v_cndmask_b32_e32 v36, v36, v96, vcc
	v_pk_fma_f32 v[112:113], v[68:69], v[92:93], v[112:113] op_sel_hi:[1,0,1]
	v_pk_fma_f32 v[114:115], v[70:71], v[92:93], v[114:115] op_sel_hi:[1,0,1]
	v_pk_fma_f32 v[116:117], v[72:73], v[92:93], v[116:117] op_sel_hi:[1,0,1]
	v_pk_fma_f32 v[118:119], v[74:75], v[92:93], v[118:119] op_sel_hi:[1,0,1]
	v_pk_fma_f32 v[120:121], v[76:77], v[92:93], v[120:121] op_sel_hi:[1,0,1]
	v_pk_fma_f32 v[122:123], v[78:79], v[92:93], v[122:123] op_sel_hi:[1,0,1]
	ds_read_b128 v[64:67], v159 offset:14848
	ds_read_b128 v[48:51], v159 offset:14336
	ds_read_b128 v[68:71], v159 offset:14864
	ds_read_b128 v[52:55], v159 offset:14352
	ds_read_b128 v[72:75], v159 offset:14880
	ds_read_b128 v[56:59], v159 offset:14368
	ds_read_b128 v[76:79], v159 offset:14896
	s_waitcnt lgkmcnt(7)
	v_pk_mul_f32 v[86:87], v[108:109], v[194:195]
	v_pk_mul_f32 v[88:89], v[108:109], v[178:179]
	v_pk_fma_f32 v[86:87], v[110:111], v[196:197], v[86:87]
	v_pk_fma_f32 v[88:89], v[110:111], v[180:181], v[88:89]
	v_pk_fma_f32 v[86:87], v[112:113], v[198:199], v[86:87]
	v_pk_fma_f32 v[88:89], v[112:113], v[182:183], v[88:89]
	v_mul_f32_e32 v90, v80, v210
	v_mul_f32_e32 v91, v83, v213
	v_pk_fma_f32 v[86:87], v[114:115], v[200:201], v[86:87]
	v_pk_fma_f32 v[88:89], v[114:115], v[184:185], v[88:89]
	v_pk_fma_f32 v[86:87], v[116:117], v[202:203], v[86:87]
	v_pk_fma_f32 v[88:89], v[116:117], v[186:187], v[88:89]
	v_pk_fma_f32 v[86:87], v[118:119], v[204:205], v[86:87]
	v_pk_fma_f32 v[88:89], v[118:119], v[188:189], v[88:89]
	v_pk_fma_f32 v[86:87], v[120:121], v[206:207], v[86:87]
	v_pk_fma_f32 v[88:89], v[120:121], v[190:191], v[88:89]
	v_pk_fma_f32 v[86:87], v[122:123], v[208:209], v[86:87]
	v_pk_fma_f32 v[88:89], v[122:123], v[192:193], v[88:89]
	v_add_f32_e32 v86, v86, v87
	v_add_f32_e32 v88, v88, v89
	ds_read_b128 v[60:63], v159 offset:14384
	v_add_f32_dpp v86, v86, v86 row_half_mirror row_mask:0xf bank_mask:0xf bound_ctrl:1
	v_add_f32_dpp v88, v88, v88 row_half_mirror row_mask:0xf bank_mask:0xf bound_ctrl:1
	ds_read_b128 v[80:83], v97 offset:224
	v_add_f32_dpp v86, v86, v86 quad_perm:[2,3,0,1] row_mask:0xf bank_mask:0xf bound_ctrl:1
	v_add_f32_dpp v88, v88, v88 quad_perm:[2,3,0,1] row_mask:0xf bank_mask:0xf bound_ctrl:1
	ds_read_b32 v84, v160 offset:17280
	v_add_f32_dpp v86, v86, v86 quad_perm:[1,0,3,2] row_mask:0xf bank_mask:0xf bound_ctrl:1
	v_add_f32_dpp v88, v88, v88 quad_perm:[1,0,3,2] row_mask:0xf bank_mask:0xf bound_ctrl:1
	v_fma_f32 v94, -v90, v86, v214
	v_mul_f32_e32 v95, v90, v88
	v_mul_f32_e32 v94, v211, v94
	v_cmp_eq_u32_e32 vcc, 5, v156
	v_mul_f32_e32 v92, v94, v91
	v_fma_f32 v96, v212, v94, v95
	v_pk_fma_f32 v[108:109], v[194:195], v[92:93], v[108:109] op_sel_hi:[1,0,1]
	v_pk_fma_f32 v[110:111], v[196:197], v[92:93], v[110:111] op_sel_hi:[1,0,1]
	v_cndmask_b32_e32 v36, v36, v96, vcc
	v_pk_fma_f32 v[112:113], v[198:199], v[92:93], v[112:113] op_sel_hi:[1,0,1]
	v_pk_fma_f32 v[114:115], v[200:201], v[92:93], v[114:115] op_sel_hi:[1,0,1]
	v_pk_fma_f32 v[116:117], v[202:203], v[92:93], v[116:117] op_sel_hi:[1,0,1]
	v_pk_fma_f32 v[118:119], v[204:205], v[92:93], v[118:119] op_sel_hi:[1,0,1]
	v_pk_fma_f32 v[120:121], v[206:207], v[92:93], v[120:121] op_sel_hi:[1,0,1]
	v_pk_fma_f32 v[122:123], v[208:209], v[92:93], v[122:123] op_sel_hi:[1,0,1]
	ds_read_b128 v[194:197], v159 offset:15872
	ds_read_b128 v[178:181], v159 offset:15360
	ds_read_b128 v[198:201], v159 offset:15888
	ds_read_b128 v[182:185], v159 offset:15376
	ds_read_b128 v[202:205], v159 offset:15904
	ds_read_b128 v[186:189], v159 offset:15392
	ds_read_b128 v[206:209], v159 offset:15920
	s_waitcnt lgkmcnt(7)
; __device__ __forceinline__ f32x2 fma2(f32x2 a, f32x2 b, f32x2 c) { return __builtin_elementwise_fma(a, b, c); }
; __device__ __forceinline__ float sum8(float x) { x += dppf<0x141>(x); x += dppf<0x4E>(x); x += dppf<0xB1>(x); return x; }
; template <int TB> __device__ __forceinline__ void gdn_block8(f32x2 (&S)[8], const LAS float* B, int kq, int vidx, float* oo) {
;     ...
;     for (int t0 = 0; t0 < TB; t0 += SCAN_UNR) {
;         float P = 1.f, iP = 1.f;
; #pragma unroll
;         for (int tt = 0; tt < SCAN_UNR; ++tt) {
;             const int t = t0 + tt;
;             const GOps8 n = g_ld8(B, (t + 1) & 15, kq, vidx);
;             const f32x2 k[8] = PAIRS8(c.k), q[8] = PAIRS8(c.q);
;             f32x2 pk = S[0] * k[0], pq = S[0] * q[0];
; #pragma unroll
;             for (int e = 1; e < 8; ++e) { pk = fma2(S[e], k[e], pk); pq = fma2(S[e], q[e], pq); }
;             const float dk = sum8(pk.x + pk.y), dq = sum8(pq.x + pq.y);
;             P *= c.sc.x; iP *= c.sc.w;
;             const float coef = c.sc.y * (c.v - P * dk);
;             const float cs = coef * iP; const f32x2 cf2 = {cs, cs};
; #pragma unroll
;             for (int e = 0; e < 8; ++e) S[e] = fma2(k[e], cf2, S[e]);
;             const float o = P * dq + c.sc.z * coef;
;             okA = (kq == t) ? o : okA; okB = (kq + 8 == t) ? o : okB;
;             c = n;
;         }
;         const f32x2 p2 = {P, P};
; #pragma unroll
;         for (int e = 0; e < 8; ++e) S[e] = S[e] * p2;
;     }
;     oo[(size_t)kq * GW] = okA;
;     if (TB == 16) oo[(size_t)(kq + 8) * GW] = okB;
	v_pk_mul_f32 v[86:87], v[108:109], v[64:65]
	v_pk_mul_f32 v[88:89], v[108:109], v[48:49]
	v_pk_fma_f32 v[86:87], v[110:111], v[66:67], v[86:87]
	v_pk_fma_f32 v[88:89], v[110:111], v[50:51], v[88:89]
	v_pk_fma_f32 v[86:87], v[112:113], v[68:69], v[86:87]
	v_pk_fma_f32 v[88:89], v[112:113], v[52:53], v[88:89]
	v_mul_f32_e32 v90, v90, v80
	v_mul_f32_e32 v91, v91, v83
	v_pk_fma_f32 v[86:87], v[114:115], v[70:71], v[86:87]
	v_pk_fma_f32 v[88:89], v[114:115], v[54:55], v[88:89]
	v_pk_fma_f32 v[86:87], v[116:117], v[72:73], v[86:87]
	v_pk_fma_f32 v[88:89], v[116:117], v[56:57], v[88:89]
	v_pk_fma_f32 v[86:87], v[118:119], v[74:75], v[86:87]
	v_pk_fma_f32 v[88:89], v[118:119], v[58:59], v[88:89]
	v_pk_fma_f32 v[86:87], v[120:121], v[76:77], v[86:87]
	v_pk_fma_f32 v[88:89], v[120:121], v[60:61], v[88:89]
	v_pk_fma_f32 v[86:87], v[122:123], v[78:79], v[86:87]
	v_pk_fma_f32 v[88:89], v[122:123], v[62:63], v[88:89]
	v_add_f32_e32 v86, v86, v87
	v_add_f32_e32 v88, v88, v89
	ds_read_b128 v[190:193], v159 offset:15408
	v_add_f32_dpp v86, v86, v86 row_half_mirror row_mask:0xf bank_mask:0xf bound_ctrl:1
	v_add_f32_dpp v88, v88, v88 row_half_mirror row_mask:0xf bank_mask:0xf bound_ctrl:1
	ds_read_b128 v[210:213], v97 offset:240
	v_add_f32_dpp v86, v86, v86 quad_perm:[2,3,0,1] row_mask:0xf bank_mask:0xf bound_ctrl:1
	v_add_f32_dpp v88, v88, v88 quad_perm:[2,3,0,1] row_mask:0xf bank_mask:0xf bound_ctrl:1
	ds_read_b32 v214, v160 offset:17344
	v_add_f32_dpp v86, v86, v86 quad_perm:[1,0,3,2] row_mask:0xf bank_mask:0xf bound_ctrl:1
	v_add_f32_dpp v88, v88, v88 quad_perm:[1,0,3,2] row_mask:0xf bank_mask:0xf bound_ctrl:1
	v_fma_f32 v94, -v90, v86, v84
	v_mul_f32_e32 v95, v90, v88
	v_mul_f32_e32 v94, v81, v94
	v_cmp_eq_u32_e32 vcc, 6, v156
	v_mul_f32_e32 v92, v94, v91
	v_fma_f32 v96, v82, v94, v95
	v_pk_fma_f32 v[108:109], v[64:65], v[92:93], v[108:109] op_sel_hi:[1,0,1]
	v_pk_fma_f32 v[110:111], v[66:67], v[92:93], v[110:111] op_sel_hi:[1,0,1]
	v_cndmask_b32_e32 v36, v36, v96, vcc
	v_pk_fma_f32 v[112:113], v[68:69], v[92:93], v[112:113] op_sel_hi:[1,0,1]
	v_pk_fma_f32 v[114:115], v[70:71], v[92:93], v[114:115] op_sel_hi:[1,0,1]
	v_pk_fma_f32 v[116:117], v[72:73], v[92:93], v[116:117] op_sel_hi:[1,0,1]
	v_pk_fma_f32 v[118:119], v[74:75], v[92:93], v[118:119] op_sel_hi:[1,0,1]
	v_pk_fma_f32 v[120:121], v[76:77], v[92:93], v[120:121] op_sel_hi:[1,0,1]
	v_pk_fma_f32 v[122:123], v[78:79], v[92:93], v[122:123] op_sel_hi:[1,0,1]
	s_waitcnt lgkmcnt(0)
	v_pk_mul_f32 v[86:87], v[108:109], v[194:195]
	v_pk_mul_f32 v[88:89], v[108:109], v[178:179]
	v_pk_fma_f32 v[86:87], v[110:111], v[196:197], v[86:87]
	v_pk_fma_f32 v[88:89], v[110:111], v[180:181], v[88:89]
	v_pk_fma_f32 v[86:87], v[112:113], v[198:199], v[86:87]
	v_pk_fma_f32 v[88:89], v[112:113], v[182:183], v[88:89]
	v_mul_f32_e32 v90, v90, v210
	v_mul_f32_e32 v91, v91, v213
	v_pk_fma_f32 v[86:87], v[114:115], v[200:201], v[86:87]
	v_pk_fma_f32 v[88:89], v[114:115], v[184:185], v[88:89]
	v_pk_fma_f32 v[86:87], v[116:117], v[202:203], v[86:87]
	v_pk_fma_f32 v[88:89], v[116:117], v[186:187], v[88:89]
	v_pk_fma_f32 v[86:87], v[118:119], v[204:205], v[86:87]
	v_pk_fma_f32 v[88:89], v[118:119], v[188:189], v[88:89]
	v_pk_fma_f32 v[86:87], v[120:121], v[206:207], v[86:87]
	v_pk_fma_f32 v[88:89], v[120:121], v[190:191], v[88:89]
	v_pk_fma_f32 v[86:87], v[122:123], v[208:209], v[86:87]
	v_pk_fma_f32 v[88:89], v[122:123], v[192:193], v[88:89]
	v_add_f32_e32 v86, v86, v87
	v_add_f32_e32 v88, v88, v89
	s_nop 0
	v_add_f32_dpp v86, v86, v86 row_half_mirror row_mask:0xf bank_mask:0xf bound_ctrl:1
	v_add_f32_dpp v88, v88, v88 row_half_mirror row_mask:0xf bank_mask:0xf bound_ctrl:1
	s_nop 0
	v_add_f32_dpp v86, v86, v86 quad_perm:[2,3,0,1] row_mask:0xf bank_mask:0xf bound_ctrl:1
	v_add_f32_dpp v88, v88, v88 quad_perm:[2,3,0,1] row_mask:0xf bank_mask:0xf bound_ctrl:1
	s_nop 0
	v_add_f32_dpp v86, v86, v86 quad_perm:[1,0,3,2] row_mask:0xf bank_mask:0xf bound_ctrl:1
	v_add_f32_dpp v88, v88, v88 quad_perm:[1,0,3,2] row_mask:0xf bank_mask:0xf bound_ctrl:1
	v_fma_f32 v94, -v90, v86, v214
	v_mul_f32_e32 v95, v90, v88
	v_mul_f32_e32 v94, v211, v94
	v_cmp_eq_u32_e32 vcc, 7, v156
	v_mul_f32_e32 v92, v94, v91
	v_fma_f32 v96, v212, v94, v95
	v_pk_fma_f32 v[108:109], v[194:195], v[92:93], v[108:109] op_sel_hi:[1,0,1]
	v_pk_fma_f32 v[110:111], v[196:197], v[92:93], v[110:111] op_sel_hi:[1,0,1]
	v_cndmask_b32_e32 v36, v36, v96, vcc
	v_pk_fma_f32 v[112:113], v[198:199], v[92:93], v[112:113] op_sel_hi:[1,0,1]
	v_pk_fma_f32 v[114:115], v[200:201], v[92:93], v[114:115] op_sel_hi:[1,0,1]
	v_pk_fma_f32 v[116:117], v[202:203], v[92:93], v[116:117] op_sel_hi:[1,0,1]
	v_pk_fma_f32 v[118:119], v[204:205], v[92:93], v[118:119] op_sel_hi:[1,0,1]
	v_pk_fma_f32 v[120:121], v[206:207], v[92:93], v[120:121] op_sel_hi:[1,0,1]
	v_pk_fma_f32 v[122:123], v[208:209], v[92:93], v[122:123] op_sel_hi:[1,0,1]
	v_pk_mul_f32 v[108:109], v[90:91], v[108:109] op_sel_hi:[0,1]
	v_pk_mul_f32 v[110:111], v[90:91], v[110:111] op_sel_hi:[0,1]
	v_pk_mul_f32 v[112:113], v[90:91], v[112:113] op_sel_hi:[0,1]
	v_pk_mul_f32 v[114:115], v[90:91], v[114:115] op_sel_hi:[0,1]
	v_pk_mul_f32 v[116:117], v[90:91], v[116:117] op_sel_hi:[0,1]
	v_pk_mul_f32 v[118:119], v[90:91], v[118:119] op_sel_hi:[0,1]
	v_pk_mul_f32 v[120:121], v[90:91], v[120:121] op_sel_hi:[0,1]
	v_pk_mul_f32 v[122:123], v[90:91], v[122:123] op_sel_hi:[0,1]
	v_lshlrev_b32_e32 v28, 11, v156
	v_mov_b32_e32 v29, v3
	v_lshl_add_u64 v[0:1], v[0:1], 0, v[28:29]
	global_store_dword v[0:1], v37, off
	v_add_co_u32_e32 v0, vcc, 0x4000, v0
	v_mov_b32_e32 v29, v123
	s_nop 0
	v_addc_co_u32_e32 v1, vcc, 0, v1, vcc
	global_store_dword v[0:1], v36, off
	v_mov_b32_e32 v28, v122
	v_mov_b32_e32 v31, v121
	v_mov_b32_e32 v30, v120
	v_mov_b32_e32 v33, v119
	v_mov_b32_e32 v32, v118
	v_mov_b32_e32 v35, v117
	v_mov_b32_e32 v34, v116
	v_mov_b32_e32 v37, v115
	v_mov_b32_e32 v36, v114
	v_mov_b32_e32 v39, v113
	v_mov_b32_e32 v38, v112
	v_mov_b32_e32 v41, v111
	v_mov_b32_e32 v40, v110
	v_mov_b32_e32 v43, v109
	v_mov_b32_e32 v42, v108
	s_andn2_b64 vcc, exec, s[46:47]
	s_cbranch_vccz .LBB0_970
	s_branch .LBB0_971

; #define LAS __attribute__((address_space(3)))
; __device__ __forceinline__ f32x2 fma2(f32x2 a, f32x2 b, f32x2 c) { return __builtin_elementwise_fma(a, b, c); }
; __device__ __forceinline__ float sum8(float x) { x += dppf<0x141>(x); x += dppf<0x4E>(x); x += dppf<0xB1>(x); return x; }
; __device__ __forceinline__ ROps8 r_ld8(const LAS float* B, int t, int kq, int vidx) {
;     ROps8 o; const LAS float* V = B + t * 320 + kq * 8;
; #pragma unroll
;     for (int h = 0; h < 2; ++h) { o.u[h] = *(const LAS f32x4*)(V + 4 * h); o.a[h] = *(const LAS f32x4*)(V + 64 + 4 * h); o.b[h] = *(const LAS f32x4*)(V + 128 + 4 * h); o.k[h] = *(const LAS f32x4*)(V + 192 + 4 * h); o.w[h] = *(const LAS f32x4*)(V + 256 + 4 * h); }
;     o.v = B[5120 + t * 16 + vidx]; o.sc = *(const LAS f32x2*)(B + 5376 + t * 2); return o;
; }
; template <int TB> __device__ __forceinline__ void rwkv_block8(f32x2 (&S)[4], const LAS float* B, int kq, int vidx, float* yo) {
;     float ykA = 0.f, ykB = 0.f;
;     ROps8 c = r_ld8(B, 0, kq, vidx);
; #pragma unroll 1
;     for (int t0 = 0; t0 < TB; t0 += SCAN_UNR)
; #pragma unroll
;     for (int tt = 0; tt < SCAN_UNR; ++tt) {
;         const int t = t0 + tt;
;         const ROps8 n = r_ld8(B, (t + 1) & 15, kq, vidx);
;         const f32x2 a[4] = PAIRS(c.a), w[4] = PAIRS(c.w), u[4] = PAIRS(c.u), b[4] = PAIRS(c.b), k[4] = PAIRS(c.k);
;         const f32x2 ps = fma2(S[3], a[3], fma2(S[2], a[2], fma2(S[1], a[1], S[0] * a[0]))), py = fma2(S[3], w[3], fma2(S[2], w[2], fma2(S[1], w[1], S[0] * w[0])));
;         const float sa = sum8(ps.x + ps.y), yp = sum8(py.x + py.y);
;         const f32x2 sa2 = {sa, sa}, v2 = {c.v, c.v};
; #pragma unroll
;         for (int e = 0; e < 4; ++e) { S[e] = fma2(-u[e], S[e], S[e]); S[e] = fma2(sa2, b[e], S[e]); S[e] = fma2(v2, k[e], S[e]); }
;         const float y = yp + sa * c.sc.x + c.v * c.sc.y;
;         ykA = (kq == t) ? y : ykA; ykB = (kq + 8 == t) ? y : ykB;
;         c = n;
;     }
;     yo[(size_t)kq * RW] = ykA;
;     if (TB == 16) yo[(size_t)(kq + 8) * RW] = ykB;
; }
.LBB0_1054:
	v_mov_b32_e32 v56, s49
	ds_read_b128 v[82:85], v145 offset:256
	ds_read_b128 v[86:89], v145 offset:272
	ds_read_b128 v[106:109], v145 offset:1024
	ds_read_b128 v[110:113], v145 offset:1040
	ds_read_b64 v[114:115], v56 offset:0
	ds_read_b32 v116, v146 offset:20480
	ds_read_b128 v[74:77], v145 offset:0
	ds_read_b128 v[78:81], v145 offset:16
	ds_read_b128 v[90:93], v145 offset:512
	ds_read_b128 v[94:97], v145 offset:528
	ds_read_b128 v[98:101], v145 offset:768
	ds_read_b128 v[102:105], v145 offset:784
	ds_read_b128 v[186:189], v145 offset:1536
	ds_read_b128 v[190:193], v145 offset:1552
	ds_read_b128 v[210:213], v145 offset:2304
	ds_read_b128 v[214:217], v145 offset:2320
	ds_read_b64 v[218:219], v56 offset:8
	ds_read_b32 v220, v146 offset:20544
	ds_read_b128 v[178:181], v145 offset:1280
	ds_read_b128 v[182:185], v145 offset:1296
	ds_read_b128 v[194:197], v145 offset:1792
	s_waitcnt lgkmcnt(9)
	v_pk_mul_f32 v[50:51], v[120:121], v[82:83]
	v_pk_mul_f32 v[52:53], v[120:121], v[106:107]
	v_pk_fma_f32 v[50:51], v[122:123], v[84:85], v[50:51]
	v_pk_fma_f32 v[52:53], v[122:123], v[108:109], v[52:53]
	v_pk_fma_f32 v[50:51], v[124:125], v[86:87], v[50:51]
	v_pk_fma_f32 v[52:53], v[124:125], v[110:111], v[52:53]
	v_pk_fma_f32 v[50:51], v[126:127], v[88:89], v[50:51]
	v_pk_fma_f32 v[52:53], v[126:127], v[112:113], v[52:53]
	v_add_f32_e32 v50, v50, v51
	v_add_f32_e32 v52, v52, v53
	ds_read_b128 v[198:201], v145 offset:1808
	v_add_f32_dpp v50, v50, v50 row_half_mirror row_mask:0xf bank_mask:0xf bound_ctrl:1
	v_add_f32_dpp v52, v52, v52 row_half_mirror row_mask:0xf bank_mask:0xf bound_ctrl:1
	ds_read_b128 v[202:205], v145 offset:2048
	v_add_f32_dpp v50, v50, v50 quad_perm:[2,3,0,1] row_mask:0xf bank_mask:0xf bound_ctrl:1
	v_add_f32_dpp v52, v52, v52 quad_perm:[2,3,0,1] row_mask:0xf bank_mask:0xf bound_ctrl:1
	ds_read_b128 v[206:209], v145 offset:2064
	v_add_f32_dpp v50, v50, v50 quad_perm:[1,0,3,2] row_mask:0xf bank_mask:0xf bound_ctrl:1
	v_add_f32_dpp v52, v52, v52 quad_perm:[1,0,3,2] row_mask:0xf bank_mask:0xf bound_ctrl:1
	v_pk_fma_f32 v[120:121], v[74:75], v[120:121], v[120:121] neg_lo:[1,0,0] neg_hi:[1,0,0]
	v_pk_fma_f32 v[122:123], v[76:77], v[122:123], v[122:123] neg_lo:[1,0,0] neg_hi:[1,0,0]
	v_pk_fma_f32 v[124:125], v[78:79], v[124:125], v[124:125] neg_lo:[1,0,0] neg_hi:[1,0,0]
	v_pk_fma_f32 v[126:127], v[80:81], v[126:127], v[126:127] neg_lo:[1,0,0] neg_hi:[1,0,0]
	v_cmp_eq_u32_e32 vcc, 0, v129
	v_pk_fma_f32 v[120:121], v[50:51], v[90:91], v[120:121] op_sel_hi:[0,1,1]
	v_fma_f32 v54, v50, v114, v52
	v_pk_fma_f32 v[122:123], v[50:51], v[92:93], v[122:123] op_sel_hi:[0,1,1]
	v_pk_fma_f32 v[124:125], v[50:51], v[94:95], v[124:125] op_sel_hi:[0,1,1]
	v_pk_fma_f32 v[126:127], v[50:51], v[96:97], v[126:127] op_sel_hi:[0,1,1]
	v_fma_f32 v55, v116, v115, v54
	v_pk_fma_f32 v[120:121], v[116:117], v[98:99], v[120:121] op_sel_hi:[0,1,1]
	v_pk_fma_f32 v[122:123], v[116:117], v[100:101], v[122:123] op_sel_hi:[0,1,1]
	v_cndmask_b32_e32 v49, v49, v55, vcc
	v_pk_fma_f32 v[124:125], v[116:117], v[102:103], v[124:125] op_sel_hi:[0,1,1]
	v_pk_fma_f32 v[126:127], v[116:117], v[104:105], v[126:127] op_sel_hi:[0,1,1]
	ds_read_b128 v[82:85], v145 offset:2816
	ds_read_b128 v[86:89], v145 offset:2832
	ds_read_b128 v[106:109], v145 offset:3584
	ds_read_b128 v[110:113], v145 offset:3600
	ds_read_b64 v[114:115], v56 offset:16
	ds_read_b32 v116, v146 offset:20608
	ds_read_b128 v[74:77], v145 offset:2560
	ds_read_b128 v[78:81], v145 offset:2576
	ds_read_b128 v[90:93], v145 offset:3072
	s_waitcnt lgkmcnt(9)
	v_pk_mul_f32 v[50:51], v[120:121], v[186:187]
	v_pk_mul_f32 v[52:53], v[120:121], v[210:211]
	v_pk_fma_f32 v[50:51], v[122:123], v[188:189], v[50:51]
	v_pk_fma_f32 v[52:53], v[122:123], v[212:213], v[52:53]
	v_pk_fma_f32 v[50:51], v[124:125], v[190:191], v[50:51]
	v_pk_fma_f32 v[52:53], v[124:125], v[214:215], v[52:53]
	v_pk_fma_f32 v[50:51], v[126:127], v[192:193], v[50:51]
	v_pk_fma_f32 v[52:53], v[126:127], v[216:217], v[52:53]
	v_add_f32_e32 v50, v50, v51
	v_add_f32_e32 v52, v52, v53
	ds_read_b128 v[94:97], v145 offset:3088
	v_add_f32_dpp v50, v50, v50 row_half_mirror row_mask:0xf bank_mask:0xf bound_ctrl:1
	v_add_f32_dpp v52, v52, v52 row_half_mirror row_mask:0xf bank_mask:0xf bound_ctrl:1
	ds_read_b128 v[98:101], v145 offset:3328
	v_add_f32_dpp v50, v50, v50 quad_perm:[2,3,0,1] row_mask:0xf bank_mask:0xf bound_ctrl:1
	v_add_f32_dpp v52, v52, v52 quad_perm:[2,3,0,1] row_mask:0xf bank_mask:0xf bound_ctrl:1
	ds_read_b128 v[102:105], v145 offset:3344
	v_add_f32_dpp v50, v50, v50 quad_perm:[1,0,3,2] row_mask:0xf bank_mask:0xf bound_ctrl:1
	v_add_f32_dpp v52, v52, v52 quad_perm:[1,0,3,2] row_mask:0xf bank_mask:0xf bound_ctrl:1
	v_pk_fma_f32 v[120:121], v[178:179], v[120:121], v[120:121] neg_lo:[1,0,0] neg_hi:[1,0,0]
	v_pk_fma_f32 v[122:123], v[180:181], v[122:123], v[122:123] neg_lo:[1,0,0] neg_hi:[1,0,0]
	v_pk_fma_f32 v[124:125], v[182:183], v[124:125], v[124:125] neg_lo:[1,0,0] neg_hi:[1,0,0]
	v_pk_fma_f32 v[126:127], v[184:185], v[126:127], v[126:127] neg_lo:[1,0,0] neg_hi:[1,0,0]
	v_cmp_eq_u32_e32 vcc, 1, v129
	v_pk_fma_f32 v[120:121], v[50:51], v[194:195], v[120:121] op_sel_hi:[0,1,1]
	v_fma_f32 v54, v50, v218, v52
	v_pk_fma_f32 v[122:123], v[50:51], v[196:197], v[122:123] op_sel_hi:[0,1,1]
	v_pk_fma_f32 v[124:125], v[50:51], v[198:199], v[124:125] op_sel_hi:[0,1,1]
	v_pk_fma_f32 v[126:127], v[50:51], v[200:201], v[126:127] op_sel_hi:[0,1,1]
	v_fma_f32 v55, v220, v219, v54
	v_pk_fma_f32 v[120:121], v[220:221], v[202:203], v[120:121] op_sel_hi:[0,1,1]
	v_pk_fma_f32 v[122:123], v[220:221], v[204:205], v[122:123] op_sel_hi:[0,1,1]
	v_cndmask_b32_e32 v49, v49, v55, vcc
	v_pk_fma_f32 v[124:125], v[220:221], v[206:207], v[124:125] op_sel_hi:[0,1,1]
	v_pk_fma_f32 v[126:127], v[220:221], v[208:209], v[126:127] op_sel_hi:[0,1,1]
	ds_read_b128 v[186:189], v145 offset:4096
	ds_read_b128 v[190:193], v145 offset:4112
	ds_read_b128 v[210:213], v145 offset:4864
	ds_read_b128 v[214:217], v145 offset:4880
	ds_read_b64 v[218:219], v56 offset:24
	ds_read_b32 v220, v146 offset:20672
	ds_read_b128 v[178:181], v145 offset:3840
	ds_read_b128 v[182:185], v145 offset:3856
	ds_read_b128 v[194:197], v145 offset:4352
	s_waitcnt lgkmcnt(9)
; __device__ __forceinline__ f32x2 fma2(f32x2 a, f32x2 b, f32x2 c) { return __builtin_elementwise_fma(a, b, c); }
; __device__ __forceinline__ float sum8(float x) { x += dppf<0x141>(x); x += dppf<0x4E>(x); x += dppf<0xB1>(x); return x; }
; template <int TB> __device__ __forceinline__ void rwkv_block8(f32x2 (&S)[4], const LAS float* B, int kq, int vidx, float* yo) {
;     ...
; #pragma unroll 1
;     for (int t0 = 0; t0 < TB; t0 += SCAN_UNR)
; #pragma unroll
;     for (int tt = 0; tt < SCAN_UNR; ++tt) {
;         const int t = t0 + tt;
;         const ROps8 n = r_ld8(B, (t + 1) & 15, kq, vidx);
;         const f32x2 a[4] = PAIRS(c.a), w[4] = PAIRS(c.w), u[4] = PAIRS(c.u), b[4] = PAIRS(c.b), k[4] = PAIRS(c.k);
;         const f32x2 ps = fma2(S[3], a[3], fma2(S[2], a[2], fma2(S[1], a[1], S[0] * a[0]))), py = fma2(S[3], w[3], fma2(S[2], w[2], fma2(S[1], w[1], S[0] * w[0])));
;         const float sa = sum8(ps.x + ps.y), yp = sum8(py.x + py.y);
;         const f32x2 sa2 = {sa, sa}, v2 = {c.v, c.v};
; #pragma unroll
;         for (int e = 0; e < 4; ++e) { S[e] = fma2(-u[e], S[e], S[e]); S[e] = fma2(sa2, b[e], S[e]); S[e] = fma2(v2, k[e], S[e]); }
;         const float y = yp + sa * c.sc.x + c.v * c.sc.y;
;         ykA = (kq == t) ? y : ykA; ykB = (kq + 8 == t) ? y : ykB;
;         c = n;
;     }
	v_pk_mul_f32 v[50:51], v[120:121], v[82:83]
	v_pk_mul_f32 v[52:53], v[120:121], v[106:107]
	v_pk_fma_f32 v[50:51], v[122:123], v[84:85], v[50:51]
	v_pk_fma_f32 v[52:53], v[122:123], v[108:109], v[52:53]
	v_pk_fma_f32 v[50:51], v[124:125], v[86:87], v[50:51]
	v_pk_fma_f32 v[52:53], v[124:125], v[110:111], v[52:53]
	v_pk_fma_f32 v[50:51], v[126:127], v[88:89], v[50:51]
	v_pk_fma_f32 v[52:53], v[126:127], v[112:113], v[52:53]
	v_add_f32_e32 v50, v50, v51
	v_add_f32_e32 v52, v52, v53
	ds_read_b128 v[198:201], v145 offset:4368
	v_add_f32_dpp v50, v50, v50 row_half_mirror row_mask:0xf bank_mask:0xf bound_ctrl:1
	v_add_f32_dpp v52, v52, v52 row_half_mirror row_mask:0xf bank_mask:0xf bound_ctrl:1
	ds_read_b128 v[202:205], v145 offset:4608
	v_add_f32_dpp v50, v50, v50 quad_perm:[2,3,0,1] row_mask:0xf bank_mask:0xf bound_ctrl:1
	v_add_f32_dpp v52, v52, v52 quad_perm:[2,3,0,1] row_mask:0xf bank_mask:0xf bound_ctrl:1
	ds_read_b128 v[206:209], v145 offset:4624
	v_add_f32_dpp v50, v50, v50 quad_perm:[1,0,3,2] row_mask:0xf bank_mask:0xf bound_ctrl:1
	v_add_f32_dpp v52, v52, v52 quad_perm:[1,0,3,2] row_mask:0xf bank_mask:0xf bound_ctrl:1
	v_pk_fma_f32 v[120:121], v[74:75], v[120:121], v[120:121] neg_lo:[1,0,0] neg_hi:[1,0,0]
	v_pk_fma_f32 v[122:123], v[76:77], v[122:123], v[122:123] neg_lo:[1,0,0] neg_hi:[1,0,0]
	v_pk_fma_f32 v[124:125], v[78:79], v[124:125], v[124:125] neg_lo:[1,0,0] neg_hi:[1,0,0]
	v_pk_fma_f32 v[126:127], v[80:81], v[126:127], v[126:127] neg_lo:[1,0,0] neg_hi:[1,0,0]
	v_cmp_eq_u32_e32 vcc, 2, v129
	v_pk_fma_f32 v[120:121], v[50:51], v[90:91], v[120:121] op_sel_hi:[0,1,1]
	v_fma_f32 v54, v50, v114, v52
	v_pk_fma_f32 v[122:123], v[50:51], v[92:93], v[122:123] op_sel_hi:[0,1,1]
	v_pk_fma_f32 v[124:125], v[50:51], v[94:95], v[124:125] op_sel_hi:[0,1,1]
	v_pk_fma_f32 v[126:127], v[50:51], v[96:97], v[126:127] op_sel_hi:[0,1,1]
	v_fma_f32 v55, v116, v115, v54
	v_pk_fma_f32 v[120:121], v[116:117], v[98:99], v[120:121] op_sel_hi:[0,1,1]
	v_pk_fma_f32 v[122:123], v[116:117], v[100:101], v[122:123] op_sel_hi:[0,1,1]
	v_cndmask_b32_e32 v49, v49, v55, vcc
	v_pk_fma_f32 v[124:125], v[116:117], v[102:103], v[124:125] op_sel_hi:[0,1,1]
	v_pk_fma_f32 v[126:127], v[116:117], v[104:105], v[126:127] op_sel_hi:[0,1,1]
	ds_read_b128 v[82:85], v145 offset:5376
	ds_read_b128 v[86:89], v145 offset:5392
	ds_read_b128 v[106:109], v145 offset:6144
	ds_read_b128 v[110:113], v145 offset:6160
	ds_read_b64 v[114:115], v56 offset:32
	ds_read_b32 v116, v146 offset:20736
	ds_read_b128 v[74:77], v145 offset:5120
	ds_read_b128 v[78:81], v145 offset:5136
	ds_read_b128 v[90:93], v145 offset:5632
	s_waitcnt lgkmcnt(9)
	v_pk_mul_f32 v[50:51], v[120:121], v[186:187]
	v_pk_mul_f32 v[52:53], v[120:121], v[210:211]
	v_pk_fma_f32 v[50:51], v[122:123], v[188:189], v[50:51]
	v_pk_fma_f32 v[52:53], v[122:123], v[212:213], v[52:53]
	v_pk_fma_f32 v[50:51], v[124:125], v[190:191], v[50:51]
	v_pk_fma_f32 v[52:53], v[124:125], v[214:215], v[52:53]
	v_pk_fma_f32 v[50:51], v[126:127], v[192:193], v[50:51]
	v_pk_fma_f32 v[52:53], v[126:127], v[216:217], v[52:53]
	v_add_f32_e32 v50, v50, v51
	v_add_f32_e32 v52, v52, v53
	ds_read_b128 v[94:97], v145 offset:5648
	v_add_f32_dpp v50, v50, v50 row_half_mirror row_mask:0xf bank_mask:0xf bound_ctrl:1
	v_add_f32_dpp v52, v52, v52 row_half_mirror row_mask:0xf bank_mask:0xf bound_ctrl:1
	ds_read_b128 v[98:101], v145 offset:5888
	v_add_f32_dpp v50, v50, v50 quad_perm:[2,3,0,1] row_mask:0xf bank_mask:0xf bound_ctrl:1
	v_add_f32_dpp v52, v52, v52 quad_perm:[2,3,0,1] row_mask:0xf bank_mask:0xf bound_ctrl:1
	ds_read_b128 v[102:105], v145 offset:5904
	v_add_f32_dpp v50, v50, v50 quad_perm:[1,0,3,2] row_mask:0xf bank_mask:0xf bound_ctrl:1
	v_add_f32_dpp v52, v52, v52 quad_perm:[1,0,3,2] row_mask:0xf bank_mask:0xf bound_ctrl:1
	v_pk_fma_f32 v[120:121], v[178:179], v[120:121], v[120:121] neg_lo:[1,0,0] neg_hi:[1,0,0]
	v_pk_fma_f32 v[122:123], v[180:181], v[122:123], v[122:123] neg_lo:[1,0,0] neg_hi:[1,0,0]
	v_pk_fma_f32 v[124:125], v[182:183], v[124:125], v[124:125] neg_lo:[1,0,0] neg_hi:[1,0,0]
	v_pk_fma_f32 v[126:127], v[184:185], v[126:127], v[126:127] neg_lo:[1,0,0] neg_hi:[1,0,0]
	v_cmp_eq_u32_e32 vcc, 3, v129
	v_pk_fma_f32 v[120:121], v[50:51], v[194:195], v[120:121] op_sel_hi:[0,1,1]
	v_fma_f32 v54, v50, v218, v52
	v_pk_fma_f32 v[122:123], v[50:51], v[196:197], v[122:123] op_sel_hi:[0,1,1]
	v_pk_fma_f32 v[124:125], v[50:51], v[198:199], v[124:125] op_sel_hi:[0,1,1]
	v_pk_fma_f32 v[126:127], v[50:51], v[200:201], v[126:127] op_sel_hi:[0,1,1]
	v_fma_f32 v55, v220, v219, v54
	v_pk_fma_f32 v[120:121], v[220:221], v[202:203], v[120:121] op_sel_hi:[0,1,1]
	v_pk_fma_f32 v[122:123], v[220:221], v[204:205], v[122:123] op_sel_hi:[0,1,1]
	v_cndmask_b32_e32 v49, v49, v55, vcc
	v_pk_fma_f32 v[124:125], v[220:221], v[206:207], v[124:125] op_sel_hi:[0,1,1]
	v_pk_fma_f32 v[126:127], v[220:221], v[208:209], v[126:127] op_sel_hi:[0,1,1]
	ds_read_b128 v[186:189], v145 offset:6656
	ds_read_b128 v[190:193], v145 offset:6672
	ds_read_b128 v[210:213], v145 offset:7424
	ds_read_b128 v[214:217], v145 offset:7440
	ds_read_b64 v[218:219], v56 offset:40
	ds_read_b32 v220, v146 offset:20800
	ds_read_b128 v[178:181], v145 offset:6400
	ds_read_b128 v[182:185], v145 offset:6416
	ds_read_b128 v[194:197], v145 offset:6912
	s_waitcnt lgkmcnt(9)
; __device__ __forceinline__ f32x2 fma2(f32x2 a, f32x2 b, f32x2 c) { return __builtin_elementwise_fma(a, b, c); }
; __device__ __forceinline__ float sum8(float x) { x += dppf<0x141>(x); x += dppf<0x4E>(x); x += dppf<0xB1>(x); return x; }
; template <int TB> __device__ __forceinline__ void rwkv_block8(f32x2 (&S)[4], const LAS float* B, int kq, int vidx, float* yo) {
;     ...
; #pragma unroll 1
;     for (int t0 = 0; t0 < TB; t0 += SCAN_UNR)
; #pragma unroll
;     for (int tt = 0; tt < SCAN_UNR; ++tt) {
;         const int t = t0 + tt;
;         const ROps8 n = r_ld8(B, (t + 1) & 15, kq, vidx);
;         const f32x2 a[4] = PAIRS(c.a), w[4] = PAIRS(c.w), u[4] = PAIRS(c.u), b[4] = PAIRS(c.b), k[4] = PAIRS(c.k);
;         const f32x2 ps = fma2(S[3], a[3], fma2(S[2], a[2], fma2(S[1], a[1], S[0] * a[0]))), py = fma2(S[3], w[3], fma2(S[2], w[2], fma2(S[1], w[1], S[0] * w[0])));
;         const float sa = sum8(ps.x + ps.y), yp = sum8(py.x + py.y);
;         const f32x2 sa2 = {sa, sa}, v2 = {c.v, c.v};
; #pragma unroll
;         for (int e = 0; e < 4; ++e) { S[e] = fma2(-u[e], S[e], S[e]); S[e] = fma2(sa2, b[e], S[e]); S[e] = fma2(v2, k[e], S[e]); }
;         const float y = yp + sa * c.sc.x + c.v * c.sc.y;
;         ykA = (kq == t) ? y : ykA; ykB = (kq + 8 == t) ? y : ykB;
;         c = n;
;     }
	v_pk_mul_f32 v[50:51], v[120:121], v[82:83]
	v_pk_mul_f32 v[52:53], v[120:121], v[106:107]
	v_pk_fma_f32 v[50:51], v[122:123], v[84:85], v[50:51]
	v_pk_fma_f32 v[52:53], v[122:123], v[108:109], v[52:53]
	v_pk_fma_f32 v[50:51], v[124:125], v[86:87], v[50:51]
	v_pk_fma_f32 v[52:53], v[124:125], v[110:111], v[52:53]
	v_pk_fma_f32 v[50:51], v[126:127], v[88:89], v[50:51]
	v_pk_fma_f32 v[52:53], v[126:127], v[112:113], v[52:53]
	v_add_f32_e32 v50, v50, v51
	v_add_f32_e32 v52, v52, v53
	ds_read_b128 v[198:201], v145 offset:6928
	v_add_f32_dpp v50, v50, v50 row_half_mirror row_mask:0xf bank_mask:0xf bound_ctrl:1
	v_add_f32_dpp v52, v52, v52 row_half_mirror row_mask:0xf bank_mask:0xf bound_ctrl:1
	ds_read_b128 v[202:205], v145 offset:7168
	v_add_f32_dpp v50, v50, v50 quad_perm:[2,3,0,1] row_mask:0xf bank_mask:0xf bound_ctrl:1
	v_add_f32_dpp v52, v52, v52 quad_perm:[2,3,0,1] row_mask:0xf bank_mask:0xf bound_ctrl:1
	ds_read_b128 v[206:209], v145 offset:7184
	v_add_f32_dpp v50, v50, v50 quad_perm:[1,0,3,2] row_mask:0xf bank_mask:0xf bound_ctrl:1
	v_add_f32_dpp v52, v52, v52 quad_perm:[1,0,3,2] row_mask:0xf bank_mask:0xf bound_ctrl:1
	v_pk_fma_f32 v[120:121], v[74:75], v[120:121], v[120:121] neg_lo:[1,0,0] neg_hi:[1,0,0]
	v_pk_fma_f32 v[122:123], v[76:77], v[122:123], v[122:123] neg_lo:[1,0,0] neg_hi:[1,0,0]
	v_pk_fma_f32 v[124:125], v[78:79], v[124:125], v[124:125] neg_lo:[1,0,0] neg_hi:[1,0,0]
	v_pk_fma_f32 v[126:127], v[80:81], v[126:127], v[126:127] neg_lo:[1,0,0] neg_hi:[1,0,0]
	v_cmp_eq_u32_e32 vcc, 4, v129
	v_pk_fma_f32 v[120:121], v[50:51], v[90:91], v[120:121] op_sel_hi:[0,1,1]
	v_fma_f32 v54, v50, v114, v52
	v_pk_fma_f32 v[122:123], v[50:51], v[92:93], v[122:123] op_sel_hi:[0,1,1]
	v_pk_fma_f32 v[124:125], v[50:51], v[94:95], v[124:125] op_sel_hi:[0,1,1]
	v_pk_fma_f32 v[126:127], v[50:51], v[96:97], v[126:127] op_sel_hi:[0,1,1]
	v_fma_f32 v55, v116, v115, v54
	v_pk_fma_f32 v[120:121], v[116:117], v[98:99], v[120:121] op_sel_hi:[0,1,1]
	v_pk_fma_f32 v[122:123], v[116:117], v[100:101], v[122:123] op_sel_hi:[0,1,1]
	v_cndmask_b32_e32 v49, v49, v55, vcc
	v_pk_fma_f32 v[124:125], v[116:117], v[102:103], v[124:125] op_sel_hi:[0,1,1]
	v_pk_fma_f32 v[126:127], v[116:117], v[104:105], v[126:127] op_sel_hi:[0,1,1]
	ds_read_b128 v[82:85], v145 offset:7936
	ds_read_b128 v[86:89], v145 offset:7952
	ds_read_b128 v[106:109], v145 offset:8704
	ds_read_b128 v[110:113], v145 offset:8720
	ds_read_b64 v[114:115], v56 offset:48
	ds_read_b32 v116, v146 offset:20864
	ds_read_b128 v[74:77], v145 offset:7680
	ds_read_b128 v[78:81], v145 offset:7696
	ds_read_b128 v[90:93], v145 offset:8192
	s_waitcnt lgkmcnt(9)
	v_pk_mul_f32 v[50:51], v[120:121], v[186:187]
	v_pk_mul_f32 v[52:53], v[120:121], v[210:211]
	v_pk_fma_f32 v[50:51], v[122:123], v[188:189], v[50:51]
	v_pk_fma_f32 v[52:53], v[122:123], v[212:213], v[52:53]
	v_pk_fma_f32 v[50:51], v[124:125], v[190:191], v[50:51]
	v_pk_fma_f32 v[52:53], v[124:125], v[214:215], v[52:53]
	v_pk_fma_f32 v[50:51], v[126:127], v[192:193], v[50:51]
	v_pk_fma_f32 v[52:53], v[126:127], v[216:217], v[52:53]
	v_add_f32_e32 v50, v50, v51
	v_add_f32_e32 v52, v52, v53
	ds_read_b128 v[94:97], v145 offset:8208
	v_add_f32_dpp v50, v50, v50 row_half_mirror row_mask:0xf bank_mask:0xf bound_ctrl:1
	v_add_f32_dpp v52, v52, v52 row_half_mirror row_mask:0xf bank_mask:0xf bound_ctrl:1
	ds_read_b128 v[98:101], v145 offset:8448
	v_add_f32_dpp v50, v50, v50 quad_perm:[2,3,0,1] row_mask:0xf bank_mask:0xf bound_ctrl:1
	v_add_f32_dpp v52, v52, v52 quad_perm:[2,3,0,1] row_mask:0xf bank_mask:0xf bound_ctrl:1
	ds_read_b128 v[102:105], v145 offset:8464
	v_add_f32_dpp v50, v50, v50 quad_perm:[1,0,3,2] row_mask:0xf bank_mask:0xf bound_ctrl:1
	v_add_f32_dpp v52, v52, v52 quad_perm:[1,0,3,2] row_mask:0xf bank_mask:0xf bound_ctrl:1
	v_pk_fma_f32 v[120:121], v[178:179], v[120:121], v[120:121] neg_lo:[1,0,0] neg_hi:[1,0,0]
	v_pk_fma_f32 v[122:123], v[180:181], v[122:123], v[122:123] neg_lo:[1,0,0] neg_hi:[1,0,0]
	v_pk_fma_f32 v[124:125], v[182:183], v[124:125], v[124:125] neg_lo:[1,0,0] neg_hi:[1,0,0]
	v_pk_fma_f32 v[126:127], v[184:185], v[126:127], v[126:127] neg_lo:[1,0,0] neg_hi:[1,0,0]
	v_cmp_eq_u32_e32 vcc, 5, v129
	v_pk_fma_f32 v[120:121], v[50:51], v[194:195], v[120:121] op_sel_hi:[0,1,1]
	v_fma_f32 v54, v50, v218, v52
	v_pk_fma_f32 v[122:123], v[50:51], v[196:197], v[122:123] op_sel_hi:[0,1,1]
	v_pk_fma_f32 v[124:125], v[50:51], v[198:199], v[124:125] op_sel_hi:[0,1,1]
	v_pk_fma_f32 v[126:127], v[50:51], v[200:201], v[126:127] op_sel_hi:[0,1,1]
	v_fma_f32 v55, v220, v219, v54
	v_pk_fma_f32 v[120:121], v[220:221], v[202:203], v[120:121] op_sel_hi:[0,1,1]
	v_pk_fma_f32 v[122:123], v[220:221], v[204:205], v[122:123] op_sel_hi:[0,1,1]
	v_cndmask_b32_e32 v49, v49, v55, vcc
	v_pk_fma_f32 v[124:125], v[220:221], v[206:207], v[124:125] op_sel_hi:[0,1,1]
	v_pk_fma_f32 v[126:127], v[220:221], v[208:209], v[126:127] op_sel_hi:[0,1,1]
	ds_read_b128 v[186:189], v145 offset:9216
	ds_read_b128 v[190:193], v145 offset:9232
	ds_read_b128 v[210:213], v145 offset:9984
	ds_read_b128 v[214:217], v145 offset:10000
	ds_read_b64 v[218:219], v56 offset:56
	ds_read_b32 v220, v146 offset:20928
	ds_read_b128 v[178:181], v145 offset:8960
	ds_read_b128 v[182:185], v145 offset:8976
	ds_read_b128 v[194:197], v145 offset:9472
	s_waitcnt lgkmcnt(9)
; __device__ __forceinline__ f32x2 fma2(f32x2 a, f32x2 b, f32x2 c) { return __builtin_elementwise_fma(a, b, c); }
; __device__ __forceinline__ float sum8(float x) { x += dppf<0x141>(x); x += dppf<0x4E>(x); x += dppf<0xB1>(x); return x; }
; template <int TB> __device__ __forceinline__ void rwkv_block8(f32x2 (&S)[4], const LAS float* B, int kq, int vidx, float* yo) {
;     ...
; #pragma unroll 1
;     for (int t0 = 0; t0 < TB; t0 += SCAN_UNR)
; #pragma unroll
;     for (int tt = 0; tt < SCAN_UNR; ++tt) {
;         const int t = t0 + tt;
;         const ROps8 n = r_ld8(B, (t + 1) & 15, kq, vidx);
;         const f32x2 a[4] = PAIRS(c.a), w[4] = PAIRS(c.w), u[4] = PAIRS(c.u), b[4] = PAIRS(c.b), k[4] = PAIRS(c.k);
;         const f32x2 ps = fma2(S[3], a[3], fma2(S[2], a[2], fma2(S[1], a[1], S[0] * a[0]))), py = fma2(S[3], w[3], fma2(S[2], w[2], fma2(S[1], w[1], S[0] * w[0])));
;         const float sa = sum8(ps.x + ps.y), yp = sum8(py.x + py.y);
;         const f32x2 sa2 = {sa, sa}, v2 = {c.v, c.v};
; #pragma unroll
;         for (int e = 0; e < 4; ++e) { S[e] = fma2(-u[e], S[e], S[e]); S[e] = fma2(sa2, b[e], S[e]); S[e] = fma2(v2, k[e], S[e]); }
;         const float y = yp + sa * c.sc.x + c.v * c.sc.y;
;         ykA = (kq == t) ? y : ykA; ykB = (kq + 8 == t) ? y : ykB;
;         c = n;
;     }
	v_pk_mul_f32 v[50:51], v[120:121], v[82:83]
	v_pk_mul_f32 v[52:53], v[120:121], v[106:107]
	v_pk_fma_f32 v[50:51], v[122:123], v[84:85], v[50:51]
	v_pk_fma_f32 v[52:53], v[122:123], v[108:109], v[52:53]
	v_pk_fma_f32 v[50:51], v[124:125], v[86:87], v[50:51]
	v_pk_fma_f32 v[52:53], v[124:125], v[110:111], v[52:53]
	v_pk_fma_f32 v[50:51], v[126:127], v[88:89], v[50:51]
	v_pk_fma_f32 v[52:53], v[126:127], v[112:113], v[52:53]
	v_add_f32_e32 v50, v50, v51
	v_add_f32_e32 v52, v52, v53
	ds_read_b128 v[198:201], v145 offset:9488
	v_add_f32_dpp v50, v50, v50 row_half_mirror row_mask:0xf bank_mask:0xf bound_ctrl:1
	v_add_f32_dpp v52, v52, v52 row_half_mirror row_mask:0xf bank_mask:0xf bound_ctrl:1
	ds_read_b128 v[202:205], v145 offset:9728
	v_add_f32_dpp v50, v50, v50 quad_perm:[2,3,0,1] row_mask:0xf bank_mask:0xf bound_ctrl:1
	v_add_f32_dpp v52, v52, v52 quad_perm:[2,3,0,1] row_mask:0xf bank_mask:0xf bound_ctrl:1
	ds_read_b128 v[206:209], v145 offset:9744
	v_add_f32_dpp v50, v50, v50 quad_perm:[1,0,3,2] row_mask:0xf bank_mask:0xf bound_ctrl:1
	v_add_f32_dpp v52, v52, v52 quad_perm:[1,0,3,2] row_mask:0xf bank_mask:0xf bound_ctrl:1
	v_pk_fma_f32 v[120:121], v[74:75], v[120:121], v[120:121] neg_lo:[1,0,0] neg_hi:[1,0,0]
	v_pk_fma_f32 v[122:123], v[76:77], v[122:123], v[122:123] neg_lo:[1,0,0] neg_hi:[1,0,0]
	v_pk_fma_f32 v[124:125], v[78:79], v[124:125], v[124:125] neg_lo:[1,0,0] neg_hi:[1,0,0]
	v_pk_fma_f32 v[126:127], v[80:81], v[126:127], v[126:127] neg_lo:[1,0,0] neg_hi:[1,0,0]
	v_cmp_eq_u32_e32 vcc, 6, v129
	v_pk_fma_f32 v[120:121], v[50:51], v[90:91], v[120:121] op_sel_hi:[0,1,1]
	v_fma_f32 v54, v50, v114, v52
	v_pk_fma_f32 v[122:123], v[50:51], v[92:93], v[122:123] op_sel_hi:[0,1,1]
	v_pk_fma_f32 v[124:125], v[50:51], v[94:95], v[124:125] op_sel_hi:[0,1,1]
	v_pk_fma_f32 v[126:127], v[50:51], v[96:97], v[126:127] op_sel_hi:[0,1,1]
	v_fma_f32 v55, v116, v115, v54
	v_pk_fma_f32 v[120:121], v[116:117], v[98:99], v[120:121] op_sel_hi:[0,1,1]
	v_pk_fma_f32 v[122:123], v[116:117], v[100:101], v[122:123] op_sel_hi:[0,1,1]
	v_cndmask_b32_e32 v49, v49, v55, vcc
	v_pk_fma_f32 v[124:125], v[116:117], v[102:103], v[124:125] op_sel_hi:[0,1,1]
	v_pk_fma_f32 v[126:127], v[116:117], v[104:105], v[126:127] op_sel_hi:[0,1,1]
	ds_read_b128 v[82:85], v145 offset:10496
	ds_read_b128 v[86:89], v145 offset:10512
	ds_read_b128 v[106:109], v145 offset:11264
	ds_read_b128 v[110:113], v145 offset:11280
	ds_read_b64 v[114:115], v56 offset:64
	ds_read_b32 v116, v146 offset:20992
	ds_read_b128 v[74:77], v145 offset:10240
	ds_read_b128 v[78:81], v145 offset:10256
	ds_read_b128 v[90:93], v145 offset:10752
	s_waitcnt lgkmcnt(9)
	v_pk_mul_f32 v[50:51], v[120:121], v[186:187]
	v_pk_mul_f32 v[52:53], v[120:121], v[210:211]
	v_pk_fma_f32 v[50:51], v[122:123], v[188:189], v[50:51]
	v_pk_fma_f32 v[52:53], v[122:123], v[212:213], v[52:53]
	v_pk_fma_f32 v[50:51], v[124:125], v[190:191], v[50:51]
	v_pk_fma_f32 v[52:53], v[124:125], v[214:215], v[52:53]
	v_pk_fma_f32 v[50:51], v[126:127], v[192:193], v[50:51]
	v_pk_fma_f32 v[52:53], v[126:127], v[216:217], v[52:53]
	v_add_f32_e32 v50, v50, v51
	v_add_f32_e32 v52, v52, v53
	ds_read_b128 v[94:97], v145 offset:10768
	v_add_f32_dpp v50, v50, v50 row_half_mirror row_mask:0xf bank_mask:0xf bound_ctrl:1
	v_add_f32_dpp v52, v52, v52 row_half_mirror row_mask:0xf bank_mask:0xf bound_ctrl:1
	ds_read_b128 v[98:101], v145 offset:11008
	v_add_f32_dpp v50, v50, v50 quad_perm:[2,3,0,1] row_mask:0xf bank_mask:0xf bound_ctrl:1
	v_add_f32_dpp v52, v52, v52 quad_perm:[2,3,0,1] row_mask:0xf bank_mask:0xf bound_ctrl:1
	ds_read_b128 v[102:105], v145 offset:11024
	v_add_f32_dpp v50, v50, v50 quad_perm:[1,0,3,2] row_mask:0xf bank_mask:0xf bound_ctrl:1
	v_add_f32_dpp v52, v52, v52 quad_perm:[1,0,3,2] row_mask:0xf bank_mask:0xf bound_ctrl:1
	v_pk_fma_f32 v[120:121], v[178:179], v[120:121], v[120:121] neg_lo:[1,0,0] neg_hi:[1,0,0]
	v_pk_fma_f32 v[122:123], v[180:181], v[122:123], v[122:123] neg_lo:[1,0,0] neg_hi:[1,0,0]
	v_pk_fma_f32 v[124:125], v[182:183], v[124:125], v[124:125] neg_lo:[1,0,0] neg_hi:[1,0,0]
	v_pk_fma_f32 v[126:127], v[184:185], v[126:127], v[126:127] neg_lo:[1,0,0] neg_hi:[1,0,0]
	v_cmp_eq_u32_e32 vcc, 7, v129
	v_pk_fma_f32 v[120:121], v[50:51], v[194:195], v[120:121] op_sel_hi:[0,1,1]
	v_fma_f32 v54, v50, v218, v52
	v_pk_fma_f32 v[122:123], v[50:51], v[196:197], v[122:123] op_sel_hi:[0,1,1]
	v_pk_fma_f32 v[124:125], v[50:51], v[198:199], v[124:125] op_sel_hi:[0,1,1]
	v_pk_fma_f32 v[126:127], v[50:51], v[200:201], v[126:127] op_sel_hi:[0,1,1]
	v_fma_f32 v55, v220, v219, v54
	v_pk_fma_f32 v[120:121], v[220:221], v[202:203], v[120:121] op_sel_hi:[0,1,1]
	v_pk_fma_f32 v[122:123], v[220:221], v[204:205], v[122:123] op_sel_hi:[0,1,1]
	v_cndmask_b32_e32 v49, v49, v55, vcc
	v_pk_fma_f32 v[124:125], v[220:221], v[206:207], v[124:125] op_sel_hi:[0,1,1]
	v_pk_fma_f32 v[126:127], v[220:221], v[208:209], v[126:127] op_sel_hi:[0,1,1]
	ds_read_b128 v[186:189], v145 offset:11776
	ds_read_b128 v[190:193], v145 offset:11792
	ds_read_b128 v[210:213], v145 offset:12544
	ds_read_b128 v[214:217], v145 offset:12560
	ds_read_b64 v[218:219], v56 offset:72
	ds_read_b32 v220, v146 offset:21056
	ds_read_b128 v[178:181], v145 offset:11520
	ds_read_b128 v[182:185], v145 offset:11536
	ds_read_b128 v[194:197], v145 offset:12032
	s_waitcnt lgkmcnt(9)
; __device__ __forceinline__ f32x2 fma2(f32x2 a, f32x2 b, f32x2 c) { return __builtin_elementwise_fma(a, b, c); }
; __device__ __forceinline__ float sum8(float x) { x += dppf<0x141>(x); x += dppf<0x4E>(x); x += dppf<0xB1>(x); return x; }
; template <int TB> __device__ __forceinline__ void rwkv_block8(f32x2 (&S)[4], const LAS float* B, int kq, int vidx, float* yo) {
;     ...
; #pragma unroll 1
;     for (int t0 = 0; t0 < TB; t0 += SCAN_UNR)
; #pragma unroll
;     for (int tt = 0; tt < SCAN_UNR; ++tt) {
;         const int t = t0 + tt;
;         const ROps8 n = r_ld8(B, (t + 1) & 15, kq, vidx);
;         const f32x2 a[4] = PAIRS(c.a), w[4] = PAIRS(c.w), u[4] = PAIRS(c.u), b[4] = PAIRS(c.b), k[4] = PAIRS(c.k);
;         const f32x2 ps = fma2(S[3], a[3], fma2(S[2], a[2], fma2(S[1], a[1], S[0] * a[0]))), py = fma2(S[3], w[3], fma2(S[2], w[2], fma2(S[1], w[1], S[0] * w[0])));
;         const float sa = sum8(ps.x + ps.y), yp = sum8(py.x + py.y);
;         const f32x2 sa2 = {sa, sa}, v2 = {c.v, c.v};
; #pragma unroll
;         for (int e = 0; e < 4; ++e) { S[e] = fma2(-u[e], S[e], S[e]); S[e] = fma2(sa2, b[e], S[e]); S[e] = fma2(v2, k[e], S[e]); }
;         const float y = yp + sa * c.sc.x + c.v * c.sc.y;
;         ykA = (kq == t) ? y : ykA; ykB = (kq + 8 == t) ? y : ykB;
;         c = n;
;     }
	v_pk_mul_f32 v[50:51], v[120:121], v[82:83]
	v_pk_mul_f32 v[52:53], v[120:121], v[106:107]
	v_pk_fma_f32 v[50:51], v[122:123], v[84:85], v[50:51]
	v_pk_fma_f32 v[52:53], v[122:123], v[108:109], v[52:53]
	v_pk_fma_f32 v[50:51], v[124:125], v[86:87], v[50:51]
	v_pk_fma_f32 v[52:53], v[124:125], v[110:111], v[52:53]
	v_pk_fma_f32 v[50:51], v[126:127], v[88:89], v[50:51]
	v_pk_fma_f32 v[52:53], v[126:127], v[112:113], v[52:53]
	v_add_f32_e32 v50, v50, v51
	v_add_f32_e32 v52, v52, v53
	ds_read_b128 v[198:201], v145 offset:12048
	v_add_f32_dpp v50, v50, v50 row_half_mirror row_mask:0xf bank_mask:0xf bound_ctrl:1
	v_add_f32_dpp v52, v52, v52 row_half_mirror row_mask:0xf bank_mask:0xf bound_ctrl:1
	ds_read_b128 v[202:205], v145 offset:12288
	v_add_f32_dpp v50, v50, v50 quad_perm:[2,3,0,1] row_mask:0xf bank_mask:0xf bound_ctrl:1
	v_add_f32_dpp v52, v52, v52 quad_perm:[2,3,0,1] row_mask:0xf bank_mask:0xf bound_ctrl:1
	ds_read_b128 v[206:209], v145 offset:12304
	v_add_f32_dpp v50, v50, v50 quad_perm:[1,0,3,2] row_mask:0xf bank_mask:0xf bound_ctrl:1
	v_add_f32_dpp v52, v52, v52 quad_perm:[1,0,3,2] row_mask:0xf bank_mask:0xf bound_ctrl:1
	v_pk_fma_f32 v[120:121], v[74:75], v[120:121], v[120:121] neg_lo:[1,0,0] neg_hi:[1,0,0]
	v_pk_fma_f32 v[122:123], v[76:77], v[122:123], v[122:123] neg_lo:[1,0,0] neg_hi:[1,0,0]
	v_pk_fma_f32 v[124:125], v[78:79], v[124:125], v[124:125] neg_lo:[1,0,0] neg_hi:[1,0,0]
	v_pk_fma_f32 v[126:127], v[80:81], v[126:127], v[126:127] neg_lo:[1,0,0] neg_hi:[1,0,0]
	v_cmp_eq_u32_e32 vcc, 0, v129
	v_pk_fma_f32 v[120:121], v[50:51], v[90:91], v[120:121] op_sel_hi:[0,1,1]
	v_fma_f32 v54, v50, v114, v52
	v_pk_fma_f32 v[122:123], v[50:51], v[92:93], v[122:123] op_sel_hi:[0,1,1]
	v_pk_fma_f32 v[124:125], v[50:51], v[94:95], v[124:125] op_sel_hi:[0,1,1]
	v_pk_fma_f32 v[126:127], v[50:51], v[96:97], v[126:127] op_sel_hi:[0,1,1]
	v_fma_f32 v55, v116, v115, v54
	v_pk_fma_f32 v[120:121], v[116:117], v[98:99], v[120:121] op_sel_hi:[0,1,1]
	v_pk_fma_f32 v[122:123], v[116:117], v[100:101], v[122:123] op_sel_hi:[0,1,1]
	v_cndmask_b32_e32 v48, v48, v55, vcc
	v_pk_fma_f32 v[124:125], v[116:117], v[102:103], v[124:125] op_sel_hi:[0,1,1]
	v_pk_fma_f32 v[126:127], v[116:117], v[104:105], v[126:127] op_sel_hi:[0,1,1]
	ds_read_b128 v[82:85], v145 offset:13056
	ds_read_b128 v[86:89], v145 offset:13072
	ds_read_b128 v[106:109], v145 offset:13824
	ds_read_b128 v[110:113], v145 offset:13840
	ds_read_b64 v[114:115], v56 offset:80
	ds_read_b32 v116, v146 offset:21120
	ds_read_b128 v[74:77], v145 offset:12800
	ds_read_b128 v[78:81], v145 offset:12816
	ds_read_b128 v[90:93], v145 offset:13312
	s_waitcnt lgkmcnt(9)
	v_pk_mul_f32 v[50:51], v[120:121], v[186:187]
	v_pk_mul_f32 v[52:53], v[120:121], v[210:211]
	v_pk_fma_f32 v[50:51], v[122:123], v[188:189], v[50:51]
	v_pk_fma_f32 v[52:53], v[122:123], v[212:213], v[52:53]
	v_pk_fma_f32 v[50:51], v[124:125], v[190:191], v[50:51]
	v_pk_fma_f32 v[52:53], v[124:125], v[214:215], v[52:53]
	v_pk_fma_f32 v[50:51], v[126:127], v[192:193], v[50:51]
	v_pk_fma_f32 v[52:53], v[126:127], v[216:217], v[52:53]
	v_add_f32_e32 v50, v50, v51
	v_add_f32_e32 v52, v52, v53
	ds_read_b128 v[94:97], v145 offset:13328
	v_add_f32_dpp v50, v50, v50 row_half_mirror row_mask:0xf bank_mask:0xf bound_ctrl:1
	v_add_f32_dpp v52, v52, v52 row_half_mirror row_mask:0xf bank_mask:0xf bound_ctrl:1
	ds_read_b128 v[98:101], v145 offset:13568
	v_add_f32_dpp v50, v50, v50 quad_perm:[2,3,0,1] row_mask:0xf bank_mask:0xf bound_ctrl:1
	v_add_f32_dpp v52, v52, v52 quad_perm:[2,3,0,1] row_mask:0xf bank_mask:0xf bound_ctrl:1
	ds_read_b128 v[102:105], v145 offset:13584
	v_add_f32_dpp v50, v50, v50 quad_perm:[1,0,3,2] row_mask:0xf bank_mask:0xf bound_ctrl:1
	v_add_f32_dpp v52, v52, v52 quad_perm:[1,0,3,2] row_mask:0xf bank_mask:0xf bound_ctrl:1
	v_pk_fma_f32 v[120:121], v[178:179], v[120:121], v[120:121] neg_lo:[1,0,0] neg_hi:[1,0,0]
	v_pk_fma_f32 v[122:123], v[180:181], v[122:123], v[122:123] neg_lo:[1,0,0] neg_hi:[1,0,0]
	v_pk_fma_f32 v[124:125], v[182:183], v[124:125], v[124:125] neg_lo:[1,0,0] neg_hi:[1,0,0]
	v_pk_fma_f32 v[126:127], v[184:185], v[126:127], v[126:127] neg_lo:[1,0,0] neg_hi:[1,0,0]
	v_cmp_eq_u32_e32 vcc, 1, v129
	v_pk_fma_f32 v[120:121], v[50:51], v[194:195], v[120:121] op_sel_hi:[0,1,1]
	v_fma_f32 v54, v50, v218, v52
	v_pk_fma_f32 v[122:123], v[50:51], v[196:197], v[122:123] op_sel_hi:[0,1,1]
	v_pk_fma_f32 v[124:125], v[50:51], v[198:199], v[124:125] op_sel_hi:[0,1,1]
	v_pk_fma_f32 v[126:127], v[50:51], v[200:201], v[126:127] op_sel_hi:[0,1,1]
	v_fma_f32 v55, v220, v219, v54
	v_pk_fma_f32 v[120:121], v[220:221], v[202:203], v[120:121] op_sel_hi:[0,1,1]
	v_pk_fma_f32 v[122:123], v[220:221], v[204:205], v[122:123] op_sel_hi:[0,1,1]
	v_cndmask_b32_e32 v48, v48, v55, vcc
	v_pk_fma_f32 v[124:125], v[220:221], v[206:207], v[124:125] op_sel_hi:[0,1,1]
	v_pk_fma_f32 v[126:127], v[220:221], v[208:209], v[126:127] op_sel_hi:[0,1,1]
	ds_read_b128 v[186:189], v145 offset:14336
	ds_read_b128 v[190:193], v145 offset:14352
	ds_read_b128 v[210:213], v145 offset:15104
	ds_read_b128 v[214:217], v145 offset:15120
	ds_read_b64 v[218:219], v56 offset:88
	ds_read_b32 v220, v146 offset:21184
	ds_read_b128 v[178:181], v145 offset:14080
	ds_read_b128 v[182:185], v145 offset:14096
	ds_read_b128 v[194:197], v145 offset:14592
	s_waitcnt lgkmcnt(9)
; __device__ __forceinline__ f32x2 fma2(f32x2 a, f32x2 b, f32x2 c) { return __builtin_elementwise_fma(a, b, c); }
; __device__ __forceinline__ float sum8(float x) { x += dppf<0x141>(x); x += dppf<0x4E>(x); x += dppf<0xB1>(x); return x; }
; template <int TB> __device__ __forceinline__ void rwkv_block8(f32x2 (&S)[4], const LAS float* B, int kq, int vidx, float* yo) {
;     ...
; #pragma unroll 1
;     for (int t0 = 0; t0 < TB; t0 += SCAN_UNR)
; #pragma unroll
;     for (int tt = 0; tt < SCAN_UNR; ++tt) {
;         const int t = t0 + tt;
;         const ROps8 n = r_ld8(B, (t + 1) & 15, kq, vidx);
;         const f32x2 a[4] = PAIRS(c.a), w[4] = PAIRS(c.w), u[4] = PAIRS(c.u), b[4] = PAIRS(c.b), k[4] = PAIRS(c.k);
;         const f32x2 ps = fma2(S[3], a[3], fma2(S[2], a[2], fma2(S[1], a[1], S[0] * a[0]))), py = fma2(S[3], w[3], fma2(S[2], w[2], fma2(S[1], w[1], S[0] * w[0])));
;         const float sa = sum8(ps.x + ps.y), yp = sum8(py.x + py.y);
;         const f32x2 sa2 = {sa, sa}, v2 = {c.v, c.v};
; #pragma unroll
;         for (int e = 0; e < 4; ++e) { S[e] = fma2(-u[e], S[e], S[e]); S[e] = fma2(sa2, b[e], S[e]); S[e] = fma2(v2, k[e], S[e]); }
;         const float y = yp + sa * c.sc.x + c.v * c.sc.y;
;         ykA = (kq == t) ? y : ykA; ykB = (kq + 8 == t) ? y : ykB;
;         c = n;
;     }
	v_pk_mul_f32 v[50:51], v[120:121], v[82:83]
	v_pk_mul_f32 v[52:53], v[120:121], v[106:107]
	v_pk_fma_f32 v[50:51], v[122:123], v[84:85], v[50:51]
	v_pk_fma_f32 v[52:53], v[122:123], v[108:109], v[52:53]
	v_pk_fma_f32 v[50:51], v[124:125], v[86:87], v[50:51]
	v_pk_fma_f32 v[52:53], v[124:125], v[110:111], v[52:53]
	v_pk_fma_f32 v[50:51], v[126:127], v[88:89], v[50:51]
	v_pk_fma_f32 v[52:53], v[126:127], v[112:113], v[52:53]
	v_add_f32_e32 v50, v50, v51
	v_add_f32_e32 v52, v52, v53
	ds_read_b128 v[198:201], v145 offset:14608
	v_add_f32_dpp v50, v50, v50 row_half_mirror row_mask:0xf bank_mask:0xf bound_ctrl:1
	v_add_f32_dpp v52, v52, v52 row_half_mirror row_mask:0xf bank_mask:0xf bound_ctrl:1
	ds_read_b128 v[202:205], v145 offset:14848
	v_add_f32_dpp v50, v50, v50 quad_perm:[2,3,0,1] row_mask:0xf bank_mask:0xf bound_ctrl:1
	v_add_f32_dpp v52, v52, v52 quad_perm:[2,3,0,1] row_mask:0xf bank_mask:0xf bound_ctrl:1
	ds_read_b128 v[206:209], v145 offset:14864
	v_add_f32_dpp v50, v50, v50 quad_perm:[1,0,3,2] row_mask:0xf bank_mask:0xf bound_ctrl:1
	v_add_f32_dpp v52, v52, v52 quad_perm:[1,0,3,2] row_mask:0xf bank_mask:0xf bound_ctrl:1
	v_pk_fma_f32 v[120:121], v[74:75], v[120:121], v[120:121] neg_lo:[1,0,0] neg_hi:[1,0,0]
	v_pk_fma_f32 v[122:123], v[76:77], v[122:123], v[122:123] neg_lo:[1,0,0] neg_hi:[1,0,0]
	v_pk_fma_f32 v[124:125], v[78:79], v[124:125], v[124:125] neg_lo:[1,0,0] neg_hi:[1,0,0]
	v_pk_fma_f32 v[126:127], v[80:81], v[126:127], v[126:127] neg_lo:[1,0,0] neg_hi:[1,0,0]
	v_cmp_eq_u32_e32 vcc, 2, v129
	v_pk_fma_f32 v[120:121], v[50:51], v[90:91], v[120:121] op_sel_hi:[0,1,1]
	v_fma_f32 v54, v50, v114, v52
	v_pk_fma_f32 v[122:123], v[50:51], v[92:93], v[122:123] op_sel_hi:[0,1,1]
	v_pk_fma_f32 v[124:125], v[50:51], v[94:95], v[124:125] op_sel_hi:[0,1,1]
	v_pk_fma_f32 v[126:127], v[50:51], v[96:97], v[126:127] op_sel_hi:[0,1,1]
	v_fma_f32 v55, v116, v115, v54
	v_pk_fma_f32 v[120:121], v[116:117], v[98:99], v[120:121] op_sel_hi:[0,1,1]
	v_pk_fma_f32 v[122:123], v[116:117], v[100:101], v[122:123] op_sel_hi:[0,1,1]
	v_cndmask_b32_e32 v48, v48, v55, vcc
	v_pk_fma_f32 v[124:125], v[116:117], v[102:103], v[124:125] op_sel_hi:[0,1,1]
	v_pk_fma_f32 v[126:127], v[116:117], v[104:105], v[126:127] op_sel_hi:[0,1,1]
	ds_read_b128 v[82:85], v145 offset:15616
	ds_read_b128 v[86:89], v145 offset:15632
	ds_read_b128 v[106:109], v145 offset:16384
	ds_read_b128 v[110:113], v145 offset:16400
	ds_read_b64 v[114:115], v56 offset:96
	ds_read_b32 v116, v146 offset:21248
	ds_read_b128 v[74:77], v145 offset:15360
	ds_read_b128 v[78:81], v145 offset:15376
	ds_read_b128 v[90:93], v145 offset:15872
	s_waitcnt lgkmcnt(9)
	v_pk_mul_f32 v[50:51], v[120:121], v[186:187]
	v_pk_mul_f32 v[52:53], v[120:121], v[210:211]
	v_pk_fma_f32 v[50:51], v[122:123], v[188:189], v[50:51]
	v_pk_fma_f32 v[52:53], v[122:123], v[212:213], v[52:53]
	v_pk_fma_f32 v[50:51], v[124:125], v[190:191], v[50:51]
	v_pk_fma_f32 v[52:53], v[124:125], v[214:215], v[52:53]
	v_pk_fma_f32 v[50:51], v[126:127], v[192:193], v[50:51]
	v_pk_fma_f32 v[52:53], v[126:127], v[216:217], v[52:53]
	v_add_f32_e32 v50, v50, v51
	v_add_f32_e32 v52, v52, v53
	ds_read_b128 v[94:97], v145 offset:15888
	v_add_f32_dpp v50, v50, v50 row_half_mirror row_mask:0xf bank_mask:0xf bound_ctrl:1
	v_add_f32_dpp v52, v52, v52 row_half_mirror row_mask:0xf bank_mask:0xf bound_ctrl:1
	ds_read_b128 v[98:101], v145 offset:16128
	v_add_f32_dpp v50, v50, v50 quad_perm:[2,3,0,1] row_mask:0xf bank_mask:0xf bound_ctrl:1
	v_add_f32_dpp v52, v52, v52 quad_perm:[2,3,0,1] row_mask:0xf bank_mask:0xf bound_ctrl:1
	ds_read_b128 v[102:105], v145 offset:16144
	v_add_f32_dpp v50, v50, v50 quad_perm:[1,0,3,2] row_mask:0xf bank_mask:0xf bound_ctrl:1
	v_add_f32_dpp v52, v52, v52 quad_perm:[1,0,3,2] row_mask:0xf bank_mask:0xf bound_ctrl:1
	v_pk_fma_f32 v[120:121], v[178:179], v[120:121], v[120:121] neg_lo:[1,0,0] neg_hi:[1,0,0]
	v_pk_fma_f32 v[122:123], v[180:181], v[122:123], v[122:123] neg_lo:[1,0,0] neg_hi:[1,0,0]
	v_pk_fma_f32 v[124:125], v[182:183], v[124:125], v[124:125] neg_lo:[1,0,0] neg_hi:[1,0,0]
	v_pk_fma_f32 v[126:127], v[184:185], v[126:127], v[126:127] neg_lo:[1,0,0] neg_hi:[1,0,0]
	v_cmp_eq_u32_e32 vcc, 3, v129
	v_pk_fma_f32 v[120:121], v[50:51], v[194:195], v[120:121] op_sel_hi:[0,1,1]
	v_fma_f32 v54, v50, v218, v52
	v_pk_fma_f32 v[122:123], v[50:51], v[196:197], v[122:123] op_sel_hi:[0,1,1]
	v_pk_fma_f32 v[124:125], v[50:51], v[198:199], v[124:125] op_sel_hi:[0,1,1]
	v_pk_fma_f32 v[126:127], v[50:51], v[200:201], v[126:127] op_sel_hi:[0,1,1]
	v_fma_f32 v55, v220, v219, v54
	v_pk_fma_f32 v[120:121], v[220:221], v[202:203], v[120:121] op_sel_hi:[0,1,1]
	v_pk_fma_f32 v[122:123], v[220:221], v[204:205], v[122:123] op_sel_hi:[0,1,1]
	v_cndmask_b32_e32 v48, v48, v55, vcc
	v_pk_fma_f32 v[124:125], v[220:221], v[206:207], v[124:125] op_sel_hi:[0,1,1]
	v_pk_fma_f32 v[126:127], v[220:221], v[208:209], v[126:127] op_sel_hi:[0,1,1]
	ds_read_b128 v[186:189], v145 offset:16896
	ds_read_b128 v[190:193], v145 offset:16912
	ds_read_b128 v[210:213], v145 offset:17664
	ds_read_b128 v[214:217], v145 offset:17680
	ds_read_b64 v[218:219], v56 offset:104
	ds_read_b32 v220, v146 offset:21312
	ds_read_b128 v[178:181], v145 offset:16640
	ds_read_b128 v[182:185], v145 offset:16656
	ds_read_b128 v[194:197], v145 offset:17152
	s_waitcnt lgkmcnt(9)
; __device__ __forceinline__ f32x2 fma2(f32x2 a, f32x2 b, f32x2 c) { return __builtin_elementwise_fma(a, b, c); }
; __device__ __forceinline__ float sum8(float x) { x += dppf<0x141>(x); x += dppf<0x4E>(x); x += dppf<0xB1>(x); return x; }
; template <int TB> __device__ __forceinline__ void rwkv_block8(f32x2 (&S)[4], const LAS float* B, int kq, int vidx, float* yo) {
;     ...
; #pragma unroll 1
;     for (int t0 = 0; t0 < TB; t0 += SCAN_UNR)
; #pragma unroll
;     for (int tt = 0; tt < SCAN_UNR; ++tt) {
;         const int t = t0 + tt;
;         const ROps8 n = r_ld8(B, (t + 1) & 15, kq, vidx);
;         const f32x2 a[4] = PAIRS(c.a), w[4] = PAIRS(c.w), u[4] = PAIRS(c.u), b[4] = PAIRS(c.b), k[4] = PAIRS(c.k);
;         const f32x2 ps = fma2(S[3], a[3], fma2(S[2], a[2], fma2(S[1], a[1], S[0] * a[0]))), py = fma2(S[3], w[3], fma2(S[2], w[2], fma2(S[1], w[1], S[0] * w[0])));
;         const float sa = sum8(ps.x + ps.y), yp = sum8(py.x + py.y);
;         const f32x2 sa2 = {sa, sa}, v2 = {c.v, c.v};
; #pragma unroll
;         for (int e = 0; e < 4; ++e) { S[e] = fma2(-u[e], S[e], S[e]); S[e] = fma2(sa2, b[e], S[e]); S[e] = fma2(v2, k[e], S[e]); }
;         const float y = yp + sa * c.sc.x + c.v * c.sc.y;
;         ykA = (kq == t) ? y : ykA; ykB = (kq + 8 == t) ? y : ykB;
;         c = n;
;     }
	v_pk_mul_f32 v[50:51], v[120:121], v[82:83]
	v_pk_mul_f32 v[52:53], v[120:121], v[106:107]
	v_pk_fma_f32 v[50:51], v[122:123], v[84:85], v[50:51]
	v_pk_fma_f32 v[52:53], v[122:123], v[108:109], v[52:53]
	v_pk_fma_f32 v[50:51], v[124:125], v[86:87], v[50:51]
	v_pk_fma_f32 v[52:53], v[124:125], v[110:111], v[52:53]
	v_pk_fma_f32 v[50:51], v[126:127], v[88:89], v[50:51]
	v_pk_fma_f32 v[52:53], v[126:127], v[112:113], v[52:53]
	v_add_f32_e32 v50, v50, v51
	v_add_f32_e32 v52, v52, v53
	ds_read_b128 v[198:201], v145 offset:17168
	v_add_f32_dpp v50, v50, v50 row_half_mirror row_mask:0xf bank_mask:0xf bound_ctrl:1
	v_add_f32_dpp v52, v52, v52 row_half_mirror row_mask:0xf bank_mask:0xf bound_ctrl:1
	ds_read_b128 v[202:205], v145 offset:17408
	v_add_f32_dpp v50, v50, v50 quad_perm:[2,3,0,1] row_mask:0xf bank_mask:0xf bound_ctrl:1
	v_add_f32_dpp v52, v52, v52 quad_perm:[2,3,0,1] row_mask:0xf bank_mask:0xf bound_ctrl:1
	ds_read_b128 v[206:209], v145 offset:17424
	v_add_f32_dpp v50, v50, v50 quad_perm:[1,0,3,2] row_mask:0xf bank_mask:0xf bound_ctrl:1
	v_add_f32_dpp v52, v52, v52 quad_perm:[1,0,3,2] row_mask:0xf bank_mask:0xf bound_ctrl:1
	v_pk_fma_f32 v[120:121], v[74:75], v[120:121], v[120:121] neg_lo:[1,0,0] neg_hi:[1,0,0]
	v_pk_fma_f32 v[122:123], v[76:77], v[122:123], v[122:123] neg_lo:[1,0,0] neg_hi:[1,0,0]
	v_pk_fma_f32 v[124:125], v[78:79], v[124:125], v[124:125] neg_lo:[1,0,0] neg_hi:[1,0,0]
	v_pk_fma_f32 v[126:127], v[80:81], v[126:127], v[126:127] neg_lo:[1,0,0] neg_hi:[1,0,0]
	v_cmp_eq_u32_e32 vcc, 4, v129
	v_pk_fma_f32 v[120:121], v[50:51], v[90:91], v[120:121] op_sel_hi:[0,1,1]
	v_fma_f32 v54, v50, v114, v52
	v_pk_fma_f32 v[122:123], v[50:51], v[92:93], v[122:123] op_sel_hi:[0,1,1]
	v_pk_fma_f32 v[124:125], v[50:51], v[94:95], v[124:125] op_sel_hi:[0,1,1]
	v_pk_fma_f32 v[126:127], v[50:51], v[96:97], v[126:127] op_sel_hi:[0,1,1]
	v_fma_f32 v55, v116, v115, v54
	v_pk_fma_f32 v[120:121], v[116:117], v[98:99], v[120:121] op_sel_hi:[0,1,1]
	v_pk_fma_f32 v[122:123], v[116:117], v[100:101], v[122:123] op_sel_hi:[0,1,1]
	v_cndmask_b32_e32 v48, v48, v55, vcc
	v_pk_fma_f32 v[124:125], v[116:117], v[102:103], v[124:125] op_sel_hi:[0,1,1]
	v_pk_fma_f32 v[126:127], v[116:117], v[104:105], v[126:127] op_sel_hi:[0,1,1]
	ds_read_b128 v[82:85], v145 offset:18176
	ds_read_b128 v[86:89], v145 offset:18192
	ds_read_b128 v[106:109], v145 offset:18944
	ds_read_b128 v[110:113], v145 offset:18960
	ds_read_b64 v[114:115], v56 offset:112
	ds_read_b32 v116, v146 offset:21376
	ds_read_b128 v[74:77], v145 offset:17920
	ds_read_b128 v[78:81], v145 offset:17936
	ds_read_b128 v[90:93], v145 offset:18432
	s_waitcnt lgkmcnt(9)
	v_pk_mul_f32 v[50:51], v[120:121], v[186:187]
	v_pk_mul_f32 v[52:53], v[120:121], v[210:211]
	v_pk_fma_f32 v[50:51], v[122:123], v[188:189], v[50:51]
	v_pk_fma_f32 v[52:53], v[122:123], v[212:213], v[52:53]
	v_pk_fma_f32 v[50:51], v[124:125], v[190:191], v[50:51]
	v_pk_fma_f32 v[52:53], v[124:125], v[214:215], v[52:53]
	v_pk_fma_f32 v[50:51], v[126:127], v[192:193], v[50:51]
	v_pk_fma_f32 v[52:53], v[126:127], v[216:217], v[52:53]
	v_add_f32_e32 v50, v50, v51
	v_add_f32_e32 v52, v52, v53
	ds_read_b128 v[94:97], v145 offset:18448
	v_add_f32_dpp v50, v50, v50 row_half_mirror row_mask:0xf bank_mask:0xf bound_ctrl:1
	v_add_f32_dpp v52, v52, v52 row_half_mirror row_mask:0xf bank_mask:0xf bound_ctrl:1
	ds_read_b128 v[98:101], v145 offset:18688
	v_add_f32_dpp v50, v50, v50 quad_perm:[2,3,0,1] row_mask:0xf bank_mask:0xf bound_ctrl:1
	v_add_f32_dpp v52, v52, v52 quad_perm:[2,3,0,1] row_mask:0xf bank_mask:0xf bound_ctrl:1
	ds_read_b128 v[102:105], v145 offset:18704
	v_add_f32_dpp v50, v50, v50 quad_perm:[1,0,3,2] row_mask:0xf bank_mask:0xf bound_ctrl:1
	v_add_f32_dpp v52, v52, v52 quad_perm:[1,0,3,2] row_mask:0xf bank_mask:0xf bound_ctrl:1
	v_pk_fma_f32 v[120:121], v[178:179], v[120:121], v[120:121] neg_lo:[1,0,0] neg_hi:[1,0,0]
	v_pk_fma_f32 v[122:123], v[180:181], v[122:123], v[122:123] neg_lo:[1,0,0] neg_hi:[1,0,0]
	v_pk_fma_f32 v[124:125], v[182:183], v[124:125], v[124:125] neg_lo:[1,0,0] neg_hi:[1,0,0]
	v_pk_fma_f32 v[126:127], v[184:185], v[126:127], v[126:127] neg_lo:[1,0,0] neg_hi:[1,0,0]
	v_cmp_eq_u32_e32 vcc, 5, v129
	v_pk_fma_f32 v[120:121], v[50:51], v[194:195], v[120:121] op_sel_hi:[0,1,1]
	v_fma_f32 v54, v50, v218, v52
	v_pk_fma_f32 v[122:123], v[50:51], v[196:197], v[122:123] op_sel_hi:[0,1,1]
	v_pk_fma_f32 v[124:125], v[50:51], v[198:199], v[124:125] op_sel_hi:[0,1,1]
	v_pk_fma_f32 v[126:127], v[50:51], v[200:201], v[126:127] op_sel_hi:[0,1,1]
	v_fma_f32 v55, v220, v219, v54
	v_pk_fma_f32 v[120:121], v[220:221], v[202:203], v[120:121] op_sel_hi:[0,1,1]
	v_pk_fma_f32 v[122:123], v[220:221], v[204:205], v[122:123] op_sel_hi:[0,1,1]
	v_cndmask_b32_e32 v48, v48, v55, vcc
	v_pk_fma_f32 v[124:125], v[220:221], v[206:207], v[124:125] op_sel_hi:[0,1,1]
	v_pk_fma_f32 v[126:127], v[220:221], v[208:209], v[126:127] op_sel_hi:[0,1,1]
	ds_read_b128 v[186:189], v145 offset:19456
	ds_read_b128 v[190:193], v145 offset:19472
	ds_read_b128 v[210:213], v145 offset:20224
	ds_read_b128 v[214:217], v145 offset:20240
	ds_read_b64 v[218:219], v56 offset:120
	ds_read_b32 v220, v146 offset:21440
	ds_read_b128 v[178:181], v145 offset:19200
	ds_read_b128 v[182:185], v145 offset:19216
	ds_read_b128 v[194:197], v145 offset:19712
	s_waitcnt lgkmcnt(9)
; __device__ __forceinline__ f32x2 fma2(f32x2 a, f32x2 b, f32x2 c) { return __builtin_elementwise_fma(a, b, c); }
; __device__ __forceinline__ float sum8(float x) { x += dppf<0x141>(x); x += dppf<0x4E>(x); x += dppf<0xB1>(x); return x; }
; template <int TB> __device__ __forceinline__ void rwkv_block8(f32x2 (&S)[4], const LAS float* B, int kq, int vidx, float* yo) {
;     ...
; #pragma unroll 1
;     for (int t0 = 0; t0 < TB; t0 += SCAN_UNR)
; #pragma unroll
;     for (int tt = 0; tt < SCAN_UNR; ++tt) {
;         const int t = t0 + tt;
;         const ROps8 n = r_ld8(B, (t + 1) & 15, kq, vidx);
;         const f32x2 a[4] = PAIRS(c.a), w[4] = PAIRS(c.w), u[4] = PAIRS(c.u), b[4] = PAIRS(c.b), k[4] = PAIRS(c.k);
;         const f32x2 ps = fma2(S[3], a[3], fma2(S[2], a[2], fma2(S[1], a[1], S[0] * a[0]))), py = fma2(S[3], w[3], fma2(S[2], w[2], fma2(S[1], w[1], S[0] * w[0])));
;         const float sa = sum8(ps.x + ps.y), yp = sum8(py.x + py.y);
;         const f32x2 sa2 = {sa, sa}, v2 = {c.v, c.v};
; #pragma unroll
;         for (int e = 0; e < 4; ++e) { S[e] = fma2(-u[e], S[e], S[e]); S[e] = fma2(sa2, b[e], S[e]); S[e] = fma2(v2, k[e], S[e]); }
;         const float y = yp + sa * c.sc.x + c.v * c.sc.y;
;         ykA = (kq == t) ? y : ykA; ykB = (kq + 8 == t) ? y : ykB;
;         c = n;
;     }
;     yo[(size_t)kq * RW] = ykA;
;     if (TB == 16) yo[(size_t)(kq + 8) * RW] = ykB;
	v_pk_mul_f32 v[50:51], v[120:121], v[82:83]
	v_pk_mul_f32 v[52:53], v[120:121], v[106:107]
	v_pk_fma_f32 v[50:51], v[122:123], v[84:85], v[50:51]
	v_pk_fma_f32 v[52:53], v[122:123], v[108:109], v[52:53]
	v_pk_fma_f32 v[50:51], v[124:125], v[86:87], v[50:51]
	v_pk_fma_f32 v[52:53], v[124:125], v[110:111], v[52:53]
	v_pk_fma_f32 v[50:51], v[126:127], v[88:89], v[50:51]
	v_pk_fma_f32 v[52:53], v[126:127], v[112:113], v[52:53]
	v_add_f32_e32 v50, v50, v51
	v_add_f32_e32 v52, v52, v53
	ds_read_b128 v[198:201], v145 offset:19728
	v_add_f32_dpp v50, v50, v50 row_half_mirror row_mask:0xf bank_mask:0xf bound_ctrl:1
	v_add_f32_dpp v52, v52, v52 row_half_mirror row_mask:0xf bank_mask:0xf bound_ctrl:1
	ds_read_b128 v[202:205], v145 offset:19968
	v_add_f32_dpp v50, v50, v50 quad_perm:[2,3,0,1] row_mask:0xf bank_mask:0xf bound_ctrl:1
	v_add_f32_dpp v52, v52, v52 quad_perm:[2,3,0,1] row_mask:0xf bank_mask:0xf bound_ctrl:1
	ds_read_b128 v[206:209], v145 offset:19984
	v_add_f32_dpp v50, v50, v50 quad_perm:[1,0,3,2] row_mask:0xf bank_mask:0xf bound_ctrl:1
	v_add_f32_dpp v52, v52, v52 quad_perm:[1,0,3,2] row_mask:0xf bank_mask:0xf bound_ctrl:1
	v_pk_fma_f32 v[120:121], v[74:75], v[120:121], v[120:121] neg_lo:[1,0,0] neg_hi:[1,0,0]
	v_pk_fma_f32 v[122:123], v[76:77], v[122:123], v[122:123] neg_lo:[1,0,0] neg_hi:[1,0,0]
	v_pk_fma_f32 v[124:125], v[78:79], v[124:125], v[124:125] neg_lo:[1,0,0] neg_hi:[1,0,0]
	v_pk_fma_f32 v[126:127], v[80:81], v[126:127], v[126:127] neg_lo:[1,0,0] neg_hi:[1,0,0]
	v_cmp_eq_u32_e32 vcc, 6, v129
	v_pk_fma_f32 v[120:121], v[50:51], v[90:91], v[120:121] op_sel_hi:[0,1,1]
	v_fma_f32 v54, v50, v114, v52
	v_pk_fma_f32 v[122:123], v[50:51], v[92:93], v[122:123] op_sel_hi:[0,1,1]
	v_pk_fma_f32 v[124:125], v[50:51], v[94:95], v[124:125] op_sel_hi:[0,1,1]
	v_pk_fma_f32 v[126:127], v[50:51], v[96:97], v[126:127] op_sel_hi:[0,1,1]
	v_fma_f32 v55, v116, v115, v54
	v_pk_fma_f32 v[120:121], v[116:117], v[98:99], v[120:121] op_sel_hi:[0,1,1]
	v_pk_fma_f32 v[122:123], v[116:117], v[100:101], v[122:123] op_sel_hi:[0,1,1]
	v_cndmask_b32_e32 v48, v48, v55, vcc
	v_pk_fma_f32 v[124:125], v[116:117], v[102:103], v[124:125] op_sel_hi:[0,1,1]
	v_pk_fma_f32 v[126:127], v[116:117], v[104:105], v[126:127] op_sel_hi:[0,1,1]
	s_waitcnt lgkmcnt(0)
	v_pk_mul_f32 v[50:51], v[120:121], v[186:187]
	v_pk_mul_f32 v[52:53], v[120:121], v[210:211]
	v_pk_fma_f32 v[50:51], v[122:123], v[188:189], v[50:51]
	v_pk_fma_f32 v[52:53], v[122:123], v[212:213], v[52:53]
	v_pk_fma_f32 v[50:51], v[124:125], v[190:191], v[50:51]
	v_pk_fma_f32 v[52:53], v[124:125], v[214:215], v[52:53]
	v_pk_fma_f32 v[50:51], v[126:127], v[192:193], v[50:51]
	v_pk_fma_f32 v[52:53], v[126:127], v[216:217], v[52:53]
	v_add_f32_e32 v50, v50, v51
	v_add_f32_e32 v52, v52, v53
	v_pk_fma_f32 v[120:121], v[178:179], v[120:121], v[120:121] neg_lo:[1,0,0] neg_hi:[1,0,0]
	v_add_f32_dpp v50, v50, v50 row_half_mirror row_mask:0xf bank_mask:0xf bound_ctrl:1
	v_add_f32_dpp v52, v52, v52 row_half_mirror row_mask:0xf bank_mask:0xf bound_ctrl:1
	v_pk_fma_f32 v[122:123], v[180:181], v[122:123], v[122:123] neg_lo:[1,0,0] neg_hi:[1,0,0]
	v_add_f32_dpp v50, v50, v50 quad_perm:[2,3,0,1] row_mask:0xf bank_mask:0xf bound_ctrl:1
	v_add_f32_dpp v52, v52, v52 quad_perm:[2,3,0,1] row_mask:0xf bank_mask:0xf bound_ctrl:1
	v_pk_fma_f32 v[124:125], v[182:183], v[124:125], v[124:125] neg_lo:[1,0,0] neg_hi:[1,0,0]
	v_add_f32_dpp v50, v50, v50 quad_perm:[1,0,3,2] row_mask:0xf bank_mask:0xf bound_ctrl:1
	v_add_f32_dpp v52, v52, v52 quad_perm:[1,0,3,2] row_mask:0xf bank_mask:0xf bound_ctrl:1
	v_pk_fma_f32 v[126:127], v[184:185], v[126:127], v[126:127] neg_lo:[1,0,0] neg_hi:[1,0,0]
	v_cmp_eq_u32_e32 vcc, 7, v129
	v_pk_fma_f32 v[120:121], v[50:51], v[194:195], v[120:121] op_sel_hi:[0,1,1]
	v_fma_f32 v54, v50, v218, v52
	v_pk_fma_f32 v[122:123], v[50:51], v[196:197], v[122:123] op_sel_hi:[0,1,1]
	v_pk_fma_f32 v[124:125], v[50:51], v[198:199], v[124:125] op_sel_hi:[0,1,1]
	v_pk_fma_f32 v[126:127], v[50:51], v[200:201], v[126:127] op_sel_hi:[0,1,1]
	v_fma_f32 v55, v220, v219, v54
	v_pk_fma_f32 v[120:121], v[220:221], v[202:203], v[120:121] op_sel_hi:[0,1,1]
	v_pk_fma_f32 v[122:123], v[220:221], v[204:205], v[122:123] op_sel_hi:[0,1,1]
	v_cndmask_b32_e32 v48, v48, v55, vcc
	v_pk_fma_f32 v[124:125], v[220:221], v[206:207], v[124:125] op_sel_hi:[0,1,1]
	v_pk_fma_f32 v[126:127], v[220:221], v[208:209], v[126:127] op_sel_hi:[0,1,1]
	v_lshlrev_b32_e32 v2, 11, v129
	v_lshl_add_u64 v[36:37], v[130:131], 0, v[2:3]
	global_store_dword v[36:37], v49, off
	v_add_co_u32_e32 v36, vcc, 0x4000, v36
	v_mov_b32_e32 v39, v127
	s_nop 0
	v_addc_co_u32_e32 v37, vcc, 0, v37, vcc
	global_store_dword v[36:37], v48, off
	v_mov_b32_e32 v38, v126
	v_mov_b32_e32 v37, v125
	v_mov_b32_e32 v36, v124
	v_mov_b32_e32 v43, v123
	v_mov_b32_e32 v42, v122
	v_mov_b32_e32 v41, v121
	v_mov_b32_e32 v40, v120
	s_andn2_b64 vcc, exec, s[44:45]
	s_cbranch_vccz .LBB0_1040
	s_branch .LBB0_1041
